# gmlp_in V epilogue: packed gelu, base+imm VgT stores, DPP row statistics
# speedup vs baseline: 1.0026x; 1.0026x over previous
.LBB0_120:
	v_lshl_add_u32 v136, s58, 2, v147
	v_mul_f32_e32 v129, 0x3d372713, v124
	v_mul_f32_e32 v134, 0x3d372713, v125
	v_mul_f32_e32 v137, 0x3d372713, v126
	v_mul_f32_e32 v138, 0x3d372713, v127
	v_mul_f32_e32 v139, 0x3d372713, v116
	v_mul_f32_e32 v142, 0x3d372713, v117
	v_mul_f32_e32 v145, 0x3d372713, v118
	v_mul_f32_e32 v155, 0x3d372713, v119
	v_mul_f32_e32 v156, 0x3d372713, v108
	v_mul_f32_e32 v157, 0x3d372713, v109
	v_mul_f32_e32 v158, 0x3d372713, v110
	v_mul_f32_e32 v159, 0x3d372713, v111
	v_mul_f32_e32 v160, 0x3d372713, v100
	v_mul_f32_e32 v161, 0x3d372713, v101
	v_mul_f32_e32 v162, 0x3d372713, v102
	v_mul_f32_e32 v169, 0x3d372713, v103
	v_mul_f32_e32 v170, 0x3d372713, v92
	v_mul_f32_e32 v171, 0x3d372713, v93
	v_mul_f32_e32 v172, 0x3d372713, v94
	v_mul_f32_e32 v173, 0x3d372713, v95
	s_lshl_b32 s88, s86, 8
	v_cmp_lt_i32_e32 vcc, 63, v136
	v_mul_f32_e32 v135, v124, v129
	v_mul_f32_e32 v144, v125, v134
	v_mul_f32_e32 v141, v126, v137
	v_mul_f32_e32 v140, v127, v138
	v_mul_f32_e32 v143, v116, v139
	v_mul_f32_e32 v142, v117, v142
	v_mul_f32_e32 v139, v118, v145
	v_mul_f32_e32 v138, v119, v155
	v_mul_f32_e32 v168, v108, v156
	v_mul_f32_e32 v167, v109, v157
	v_mul_f32_e32 v166, v110, v158
	v_mul_f32_e32 v165, v111, v159
	v_mul_f32_e32 v164, v100, v160
	v_mul_f32_e32 v163, v101, v161
	v_mul_f32_e32 v162, v102, v162
	v_mul_f32_e32 v161, v103, v169
	v_mul_f32_e32 v160, v92, v170
	v_mul_f32_e32 v159, v93, v171
	v_mul_f32_e32 v158, v94, v172
	v_mul_f32_e32 v157, v95, v173
	v_mul_f32_e32 v156, 0x3d372713, v84
	v_mul_f32_e32 v155, 0x3d372713, v85
	v_mul_f32_e32 v137, 0x3d372713, v86
	v_mul_f32_e32 v129, 0x3d372713, v87
	s_and_saveexec_b64 s[58:59], vcc
	s_xor_b64 s[58:59], exec, s[58:59]
	s_cbranch_execz .LBB0_128
	v_subrev_u32_e32 v136, 64, v136
	v_add_u32_e32 v129, s88, v151
	v_lshlrev_b32_e32 v129, 8, v129
	v_lshl_add_u32 v129, v136, 3, v129
	v_lshl_add_u32 v164, s95, 1, v146
	v_ashrrev_i32_e32 v165, 31, v164
	v_lshlrev_b64 v[164:165], 19, v[164:165]
	v_lshl_add_u64 v[164:165], v[130:131], 0, v[164:165]
	v_lshl_or_b32 v166, v136, 6, v148
	v_mov_b32_e32 v167, 0
	v_lshlrev_b64 v[166:167], 8, v[166:167]
	v_lshl_add_u64 v[156:157], v[164:165], 0, v[166:167]
	s_mov_b64 s[60:61], 0x1000
	v_lshl_add_u64 v[158:159], v[156:157], 0, s[60:61]
	v_lshl_add_u64 v[160:161], v[158:159], 0, s[60:61]
	v_lshl_add_u64 v[162:163], v[160:161], 0, s[60:61]
	v_mov_b32_e32 v168, 0xc0135761
	v_mov_b32_e32 v169, 0xc0135761
	v_mov_b32_e32 v170, 0xbdd2d3e7
	v_mov_b32_e32 v171, 0xbdd2d3e7
	v_mov_b32_e32 v172, 0x3f800000
	v_mov_b32_e32 v173, 0x3f800000
	v_pk_mul_f32 v[174:175], v[124:125], v[124:125]
	v_pk_mul_f32 v[176:177], v[126:127], v[126:127]
	v_pk_fma_f32 v[174:175], v[174:175], v[170:171], v[168:169]
	v_pk_fma_f32 v[176:177], v[176:177], v[170:171], v[168:169]
	v_pk_mul_f32 v[174:175], v[124:125], v[174:175]
	v_pk_mul_f32 v[176:177], v[126:127], v[176:177]
	v_exp_f32_e32 v174, v174
	v_exp_f32_e32 v175, v175
	v_exp_f32_e32 v176, v176
	v_exp_f32_e32 v177, v177
	v_pk_add_f32 v[174:175], v[174:175], v[172:173]
	v_pk_add_f32 v[176:177], v[176:177], v[172:173]
	v_rcp_f32_e32 v174, v174
	v_rcp_f32_e32 v175, v175
	v_rcp_f32_e32 v176, v176
	v_rcp_f32_e32 v177, v177
	v_pk_mul_f32 v[174:175], v[124:125], v[174:175]
	v_pk_mul_f32 v[176:177], v[126:127], v[176:177]
	v_cvt_pk_bf16_f32 v178, v174, v175
	v_cvt_pk_bf16_f32 v179, v176, v177
	global_store_dwordx2 v[156:157], v[178:179], off
	ds_write_b16 v150, v178
	ds_write_b16_d16_hi v150, v178 offset:144
	ds_write_b16 v150, v179 offset:288
	ds_write_b16_d16_hi v150, v179 offset:432
	v_pk_mul_f32 v[174:175], v[116:117], v[116:117]
	v_pk_mul_f32 v[176:177], v[118:119], v[118:119]
	v_pk_fma_f32 v[174:175], v[174:175], v[170:171], v[168:169]
	v_pk_fma_f32 v[176:177], v[176:177], v[170:171], v[168:169]
	v_pk_mul_f32 v[174:175], v[116:117], v[174:175]
	v_pk_mul_f32 v[176:177], v[118:119], v[176:177]
	v_exp_f32_e32 v174, v174
	v_exp_f32_e32 v175, v175
	v_exp_f32_e32 v176, v176
	v_exp_f32_e32 v177, v177
	v_pk_add_f32 v[174:175], v[174:175], v[172:173]
	v_pk_add_f32 v[176:177], v[176:177], v[172:173]
	v_rcp_f32_e32 v174, v174
	v_rcp_f32_e32 v175, v175
	v_rcp_f32_e32 v176, v176
	v_rcp_f32_e32 v177, v177
	v_pk_mul_f32 v[174:175], v[116:117], v[174:175]
	v_pk_mul_f32 v[176:177], v[118:119], v[176:177]
	v_cvt_pk_bf16_f32 v182, v174, v175
	v_cvt_pk_bf16_f32 v183, v176, v177
	global_store_dwordx2 v[158:159], v[182:183], off
	ds_write_b16 v150, v182 offset:32
	ds_write_b16_d16_hi v150, v182 offset:176
	ds_write_b16 v150, v183 offset:320
	ds_write_b16_d16_hi v150, v183 offset:464
	v_pk_mul_f32 v[174:175], v[120:121], v[120:121]
	v_pk_mul_f32 v[176:177], v[122:123], v[122:123]
	v_pk_fma_f32 v[174:175], v[174:175], v[170:171], v[168:169]
	v_pk_fma_f32 v[176:177], v[176:177], v[170:171], v[168:169]
	v_pk_mul_f32 v[174:175], v[120:121], v[174:175]
	v_pk_mul_f32 v[176:177], v[122:123], v[176:177]
	v_exp_f32_e32 v174, v174
	v_exp_f32_e32 v175, v175
	v_exp_f32_e32 v176, v176
	v_exp_f32_e32 v177, v177
	v_pk_add_f32 v[174:175], v[174:175], v[172:173]
	v_pk_add_f32 v[176:177], v[176:177], v[172:173]
	v_rcp_f32_e32 v174, v174
	v_rcp_f32_e32 v175, v175
	v_rcp_f32_e32 v176, v176
	v_rcp_f32_e32 v177, v177
	v_pk_mul_f32 v[174:175], v[120:121], v[174:175]
	v_pk_mul_f32 v[176:177], v[122:123], v[176:177]
	v_cvt_pk_bf16_f32 v178, v174, v175
	v_cvt_pk_bf16_f32 v179, v176, v177
	global_store_dwordx2 v[160:161], v[178:179], off
	ds_write_b16 v150, v178 offset:64
	ds_write_b16_d16_hi v150, v178 offset:208
	ds_write_b16 v150, v179 offset:352
	ds_write_b16_d16_hi v150, v179 offset:496
	v_pk_mul_f32 v[174:175], v[112:113], v[112:113]
	v_pk_mul_f32 v[176:177], v[114:115], v[114:115]
	v_pk_fma_f32 v[174:175], v[174:175], v[170:171], v[168:169]
	v_pk_fma_f32 v[176:177], v[176:177], v[170:171], v[168:169]
	v_pk_mul_f32 v[174:175], v[112:113], v[174:175]
	v_pk_mul_f32 v[176:177], v[114:115], v[176:177]
	v_exp_f32_e32 v174, v174
	v_exp_f32_e32 v175, v175
	v_exp_f32_e32 v176, v176
	v_exp_f32_e32 v177, v177
	v_pk_add_f32 v[174:175], v[174:175], v[172:173]
	v_pk_add_f32 v[176:177], v[176:177], v[172:173]
	v_rcp_f32_e32 v174, v174
	v_rcp_f32_e32 v175, v175
	v_rcp_f32_e32 v176, v176
	v_rcp_f32_e32 v177, v177
	v_pk_mul_f32 v[174:175], v[112:113], v[174:175]
	v_pk_mul_f32 v[176:177], v[114:115], v[176:177]
	v_cvt_pk_bf16_f32 v182, v174, v175
	v_cvt_pk_bf16_f32 v183, v176, v177
	global_store_dwordx2 v[162:163], v[182:183], off
	ds_write_b16 v150, v182 offset:96
	ds_write_b16_d16_hi v150, v182 offset:240
	ds_write_b16 v150, v183 offset:384
	ds_write_b16_d16_hi v150, v183 offset:528
	v_pk_mul_f32 v[174:175], v[108:109], v[108:109]
	v_pk_mul_f32 v[176:177], v[110:111], v[110:111]
	v_pk_fma_f32 v[174:175], v[174:175], v[170:171], v[168:169]
	v_pk_fma_f32 v[176:177], v[176:177], v[170:171], v[168:169]
	v_pk_mul_f32 v[174:175], v[108:109], v[174:175]
	v_pk_mul_f32 v[176:177], v[110:111], v[176:177]
	v_exp_f32_e32 v174, v174
	v_exp_f32_e32 v175, v175
	v_exp_f32_e32 v176, v176
	v_exp_f32_e32 v177, v177
	v_pk_add_f32 v[174:175], v[174:175], v[172:173]
	v_pk_add_f32 v[176:177], v[176:177], v[172:173]
	v_rcp_f32_e32 v174, v174
	v_rcp_f32_e32 v175, v175
	v_rcp_f32_e32 v176, v176
	v_rcp_f32_e32 v177, v177
	v_pk_mul_f32 v[174:175], v[108:109], v[174:175]
	v_pk_mul_f32 v[176:177], v[110:111], v[176:177]
	v_cvt_pk_bf16_f32 v178, v174, v175
	v_cvt_pk_bf16_f32 v179, v176, v177
	global_store_dwordx2 v[156:157], v[178:179], off offset:32
	ds_write_b16 v150, v178 offset:2304
	ds_write_b16_d16_hi v150, v178 offset:2448
	ds_write_b16 v150, v179 offset:2592
	ds_write_b16_d16_hi v150, v179 offset:2736
	v_pk_mul_f32 v[174:175], v[100:101], v[100:101]
	v_pk_mul_f32 v[176:177], v[102:103], v[102:103]
	v_pk_fma_f32 v[174:175], v[174:175], v[170:171], v[168:169]
	v_pk_fma_f32 v[176:177], v[176:177], v[170:171], v[168:169]
	v_pk_mul_f32 v[174:175], v[100:101], v[174:175]
	v_pk_mul_f32 v[176:177], v[102:103], v[176:177]
	v_exp_f32_e32 v174, v174
	v_exp_f32_e32 v175, v175
	v_exp_f32_e32 v176, v176
	v_exp_f32_e32 v177, v177
	v_pk_add_f32 v[174:175], v[174:175], v[172:173]
	v_pk_add_f32 v[176:177], v[176:177], v[172:173]
	v_rcp_f32_e32 v174, v174
	v_rcp_f32_e32 v175, v175
	v_rcp_f32_e32 v176, v176
	v_rcp_f32_e32 v177, v177
	v_pk_mul_f32 v[174:175], v[100:101], v[174:175]
	v_pk_mul_f32 v[176:177], v[102:103], v[176:177]
	v_cvt_pk_bf16_f32 v182, v174, v175
	v_cvt_pk_bf16_f32 v183, v176, v177
	global_store_dwordx2 v[158:159], v[182:183], off offset:32
	ds_write_b16 v150, v182 offset:2336
	ds_write_b16_d16_hi v150, v182 offset:2480
	ds_write_b16 v150, v183 offset:2624
	ds_write_b16_d16_hi v150, v183 offset:2768
	v_pk_mul_f32 v[174:175], v[104:105], v[104:105]
	v_pk_mul_f32 v[176:177], v[106:107], v[106:107]
	v_pk_fma_f32 v[174:175], v[174:175], v[170:171], v[168:169]
	v_pk_fma_f32 v[176:177], v[176:177], v[170:171], v[168:169]
	v_pk_mul_f32 v[174:175], v[104:105], v[174:175]
	v_pk_mul_f32 v[176:177], v[106:107], v[176:177]
	v_exp_f32_e32 v174, v174
	v_exp_f32_e32 v175, v175
	v_exp_f32_e32 v176, v176
	v_exp_f32_e32 v177, v177
	v_pk_add_f32 v[174:175], v[174:175], v[172:173]
	v_pk_add_f32 v[176:177], v[176:177], v[172:173]
	v_rcp_f32_e32 v174, v174
	v_rcp_f32_e32 v175, v175
	v_rcp_f32_e32 v176, v176
	v_rcp_f32_e32 v177, v177
	v_pk_mul_f32 v[174:175], v[104:105], v[174:175]
	v_pk_mul_f32 v[176:177], v[106:107], v[176:177]
	v_cvt_pk_bf16_f32 v178, v174, v175
	v_cvt_pk_bf16_f32 v179, v176, v177
	global_store_dwordx2 v[160:161], v[178:179], off offset:32
	ds_write_b16 v150, v178 offset:2368
	ds_write_b16_d16_hi v150, v178 offset:2512
	ds_write_b16 v150, v179 offset:2656
	ds_write_b16_d16_hi v150, v179 offset:2800
	v_pk_mul_f32 v[174:175], v[96:97], v[96:97]
	v_pk_mul_f32 v[176:177], v[98:99], v[98:99]
	v_pk_fma_f32 v[174:175], v[174:175], v[170:171], v[168:169]
	v_pk_fma_f32 v[176:177], v[176:177], v[170:171], v[168:169]
	v_pk_mul_f32 v[174:175], v[96:97], v[174:175]
	v_pk_mul_f32 v[176:177], v[98:99], v[176:177]
	v_exp_f32_e32 v174, v174
	v_exp_f32_e32 v175, v175
	v_exp_f32_e32 v176, v176
	v_exp_f32_e32 v177, v177
	v_pk_add_f32 v[174:175], v[174:175], v[172:173]
	v_pk_add_f32 v[176:177], v[176:177], v[172:173]
	v_rcp_f32_e32 v174, v174
	v_rcp_f32_e32 v175, v175
	v_rcp_f32_e32 v176, v176
	v_rcp_f32_e32 v177, v177
	v_pk_mul_f32 v[174:175], v[96:97], v[174:175]
	v_pk_mul_f32 v[176:177], v[98:99], v[176:177]
	v_cvt_pk_bf16_f32 v182, v174, v175
	v_cvt_pk_bf16_f32 v183, v176, v177
	global_store_dwordx2 v[162:163], v[182:183], off offset:32
	ds_write_b16 v150, v182 offset:2400
	ds_write_b16_d16_hi v150, v182 offset:2544
	ds_write_b16 v150, v183 offset:2688
	ds_write_b16_d16_hi v150, v183 offset:2832
	v_pk_mul_f32 v[174:175], v[92:93], v[92:93]
	v_pk_mul_f32 v[176:177], v[94:95], v[94:95]
	v_pk_fma_f32 v[174:175], v[174:175], v[170:171], v[168:169]
	v_pk_fma_f32 v[176:177], v[176:177], v[170:171], v[168:169]
	v_pk_mul_f32 v[174:175], v[92:93], v[174:175]
	v_pk_mul_f32 v[176:177], v[94:95], v[176:177]
	v_exp_f32_e32 v174, v174
	v_exp_f32_e32 v175, v175
	v_exp_f32_e32 v176, v176
	v_exp_f32_e32 v177, v177
	v_pk_add_f32 v[174:175], v[174:175], v[172:173]
	v_pk_add_f32 v[176:177], v[176:177], v[172:173]
	v_rcp_f32_e32 v174, v174
	v_rcp_f32_e32 v175, v175
	v_rcp_f32_e32 v176, v176
	v_rcp_f32_e32 v177, v177
	v_pk_mul_f32 v[174:175], v[92:93], v[174:175]
	v_pk_mul_f32 v[176:177], v[94:95], v[176:177]
	v_cvt_pk_bf16_f32 v178, v174, v175
	v_cvt_pk_bf16_f32 v179, v176, v177
	global_store_dwordx2 v[156:157], v[178:179], off offset:64
	ds_write_b16 v150, v178 offset:4608
	ds_write_b16_d16_hi v150, v178 offset:4752
	ds_write_b16 v150, v179 offset:4896
	ds_write_b16_d16_hi v150, v179 offset:5040
	v_pk_mul_f32 v[174:175], v[84:85], v[84:85]
	v_pk_mul_f32 v[176:177], v[86:87], v[86:87]
	v_pk_fma_f32 v[174:175], v[174:175], v[170:171], v[168:169]
	v_pk_fma_f32 v[176:177], v[176:177], v[170:171], v[168:169]
	v_pk_mul_f32 v[174:175], v[84:85], v[174:175]
	v_pk_mul_f32 v[176:177], v[86:87], v[176:177]
	v_exp_f32_e32 v174, v174
	v_exp_f32_e32 v175, v175
	v_exp_f32_e32 v176, v176
	v_exp_f32_e32 v177, v177
	v_pk_add_f32 v[174:175], v[174:175], v[172:173]
	v_pk_add_f32 v[176:177], v[176:177], v[172:173]
	v_rcp_f32_e32 v174, v174
	v_rcp_f32_e32 v175, v175
	v_rcp_f32_e32 v176, v176
	v_rcp_f32_e32 v177, v177
	v_pk_mul_f32 v[174:175], v[84:85], v[174:175]
	v_pk_mul_f32 v[176:177], v[86:87], v[176:177]
	v_cvt_pk_bf16_f32 v182, v174, v175
	v_cvt_pk_bf16_f32 v183, v176, v177
	global_store_dwordx2 v[158:159], v[182:183], off offset:64
	ds_write_b16 v150, v182 offset:4640
	ds_write_b16_d16_hi v150, v182 offset:4784
	ds_write_b16 v150, v183 offset:4928
	ds_write_b16_d16_hi v150, v183 offset:5072
	v_pk_mul_f32 v[174:175], v[88:89], v[88:89]
	v_pk_mul_f32 v[176:177], v[90:91], v[90:91]
	v_pk_fma_f32 v[174:175], v[174:175], v[170:171], v[168:169]
	v_pk_fma_f32 v[176:177], v[176:177], v[170:171], v[168:169]
	v_pk_mul_f32 v[174:175], v[88:89], v[174:175]
	v_pk_mul_f32 v[176:177], v[90:91], v[176:177]
	v_exp_f32_e32 v174, v174
	v_exp_f32_e32 v175, v175
	v_exp_f32_e32 v176, v176
	v_exp_f32_e32 v177, v177
	v_pk_add_f32 v[174:175], v[174:175], v[172:173]
	v_pk_add_f32 v[176:177], v[176:177], v[172:173]
	v_rcp_f32_e32 v174, v174
	v_rcp_f32_e32 v175, v175
	v_rcp_f32_e32 v176, v176
	v_rcp_f32_e32 v177, v177
	v_pk_mul_f32 v[174:175], v[88:89], v[174:175]
	v_pk_mul_f32 v[176:177], v[90:91], v[176:177]
	v_cvt_pk_bf16_f32 v178, v174, v175
	v_cvt_pk_bf16_f32 v179, v176, v177
	global_store_dwordx2 v[160:161], v[178:179], off offset:64
	ds_write_b16 v150, v178 offset:4672
	ds_write_b16_d16_hi v150, v178 offset:4816
	ds_write_b16 v150, v179 offset:4960
	ds_write_b16_d16_hi v150, v179 offset:5104
	v_pk_mul_f32 v[174:175], v[80:81], v[80:81]
	v_pk_mul_f32 v[176:177], v[82:83], v[82:83]
	v_pk_fma_f32 v[174:175], v[174:175], v[170:171], v[168:169]
	v_pk_fma_f32 v[176:177], v[176:177], v[170:171], v[168:169]
	v_pk_mul_f32 v[174:175], v[80:81], v[174:175]
	v_pk_mul_f32 v[176:177], v[82:83], v[176:177]
	v_exp_f32_e32 v174, v174
	v_exp_f32_e32 v175, v175
	v_exp_f32_e32 v176, v176
	v_exp_f32_e32 v177, v177
	v_pk_add_f32 v[174:175], v[174:175], v[172:173]
	v_pk_add_f32 v[176:177], v[176:177], v[172:173]
	v_rcp_f32_e32 v174, v174
	v_rcp_f32_e32 v175, v175
	v_rcp_f32_e32 v176, v176
	v_rcp_f32_e32 v177, v177
	v_pk_mul_f32 v[174:175], v[80:81], v[174:175]
	v_pk_mul_f32 v[176:177], v[82:83], v[176:177]
	v_cvt_pk_bf16_f32 v182, v174, v175
	v_cvt_pk_bf16_f32 v183, v176, v177
	global_store_dwordx2 v[162:163], v[182:183], off offset:64
	ds_write_b16 v150, v182 offset:4704
	ds_write_b16_d16_hi v150, v182 offset:4848
	ds_write_b16 v150, v183 offset:4992
	ds_write_b16_d16_hi v150, v183 offset:5136
	v_pk_mul_f32 v[174:175], v[76:77], v[76:77]
	v_pk_mul_f32 v[176:177], v[78:79], v[78:79]
	v_pk_fma_f32 v[174:175], v[174:175], v[170:171], v[168:169]
	v_pk_fma_f32 v[176:177], v[176:177], v[170:171], v[168:169]
	v_pk_mul_f32 v[174:175], v[76:77], v[174:175]
	v_pk_mul_f32 v[176:177], v[78:79], v[176:177]
	v_exp_f32_e32 v174, v174
	v_exp_f32_e32 v175, v175
	v_exp_f32_e32 v176, v176
	v_exp_f32_e32 v177, v177
	v_pk_add_f32 v[174:175], v[174:175], v[172:173]
	v_pk_add_f32 v[176:177], v[176:177], v[172:173]
	v_rcp_f32_e32 v174, v174
	v_rcp_f32_e32 v175, v175
	v_rcp_f32_e32 v176, v176
	v_rcp_f32_e32 v177, v177
	v_pk_mul_f32 v[174:175], v[76:77], v[174:175]
	v_pk_mul_f32 v[176:177], v[78:79], v[176:177]
	v_cvt_pk_bf16_f32 v178, v174, v175
	v_cvt_pk_bf16_f32 v179, v176, v177
	global_store_dwordx2 v[156:157], v[178:179], off offset:96
	ds_write_b16 v150, v178 offset:6912
	ds_write_b16_d16_hi v150, v178 offset:7056
	ds_write_b16 v150, v179 offset:7200
	ds_write_b16_d16_hi v150, v179 offset:7344
	v_pk_mul_f32 v[174:175], v[68:69], v[68:69]
	v_pk_mul_f32 v[176:177], v[70:71], v[70:71]
	v_pk_fma_f32 v[174:175], v[174:175], v[170:171], v[168:169]
	v_pk_fma_f32 v[176:177], v[176:177], v[170:171], v[168:169]
	v_pk_mul_f32 v[174:175], v[68:69], v[174:175]
	v_pk_mul_f32 v[176:177], v[70:71], v[176:177]
	v_exp_f32_e32 v174, v174
	v_exp_f32_e32 v175, v175
	v_exp_f32_e32 v176, v176
	v_exp_f32_e32 v177, v177
	v_pk_add_f32 v[174:175], v[174:175], v[172:173]
	v_pk_add_f32 v[176:177], v[176:177], v[172:173]
	v_rcp_f32_e32 v174, v174
	v_rcp_f32_e32 v175, v175
	v_rcp_f32_e32 v176, v176
	v_rcp_f32_e32 v177, v177
	v_pk_mul_f32 v[174:175], v[68:69], v[174:175]
	v_pk_mul_f32 v[176:177], v[70:71], v[176:177]
	v_cvt_pk_bf16_f32 v182, v174, v175
	v_cvt_pk_bf16_f32 v183, v176, v177
	global_store_dwordx2 v[158:159], v[182:183], off offset:96
	ds_write_b16 v150, v182 offset:6944
	ds_write_b16_d16_hi v150, v182 offset:7088
	ds_write_b16 v150, v183 offset:7232
	ds_write_b16_d16_hi v150, v183 offset:7376
	v_pk_mul_f32 v[174:175], v[72:73], v[72:73]
	v_pk_mul_f32 v[176:177], v[74:75], v[74:75]
	v_pk_fma_f32 v[174:175], v[174:175], v[170:171], v[168:169]
	v_pk_fma_f32 v[176:177], v[176:177], v[170:171], v[168:169]
	v_pk_mul_f32 v[174:175], v[72:73], v[174:175]
	v_pk_mul_f32 v[176:177], v[74:75], v[176:177]
	v_exp_f32_e32 v174, v174
	v_exp_f32_e32 v175, v175
	v_exp_f32_e32 v176, v176
	v_exp_f32_e32 v177, v177
	v_pk_add_f32 v[174:175], v[174:175], v[172:173]
	v_pk_add_f32 v[176:177], v[176:177], v[172:173]
	v_rcp_f32_e32 v174, v174
	v_rcp_f32_e32 v175, v175
	v_rcp_f32_e32 v176, v176
	v_rcp_f32_e32 v177, v177
	v_pk_mul_f32 v[174:175], v[72:73], v[174:175]
	v_pk_mul_f32 v[176:177], v[74:75], v[176:177]
	v_cvt_pk_bf16_f32 v178, v174, v175
	v_cvt_pk_bf16_f32 v179, v176, v177
	global_store_dwordx2 v[160:161], v[178:179], off offset:96
	ds_write_b16 v150, v178 offset:6976
	ds_write_b16_d16_hi v150, v178 offset:7120
	ds_write_b16 v150, v179 offset:7264
	ds_write_b16_d16_hi v150, v179 offset:7408
	v_pk_mul_f32 v[174:175], v[64:65], v[64:65]
	v_pk_mul_f32 v[176:177], v[66:67], v[66:67]
	v_pk_fma_f32 v[174:175], v[174:175], v[170:171], v[168:169]
	v_pk_fma_f32 v[176:177], v[176:177], v[170:171], v[168:169]
	v_pk_mul_f32 v[174:175], v[64:65], v[174:175]
	v_pk_mul_f32 v[176:177], v[66:67], v[176:177]
	v_exp_f32_e32 v174, v174
	v_exp_f32_e32 v175, v175
	v_exp_f32_e32 v176, v176
	v_exp_f32_e32 v177, v177
	v_pk_add_f32 v[174:175], v[174:175], v[172:173]
	v_pk_add_f32 v[176:177], v[176:177], v[172:173]
	v_rcp_f32_e32 v174, v174
	v_rcp_f32_e32 v175, v175
	v_rcp_f32_e32 v176, v176
	v_rcp_f32_e32 v177, v177
	v_pk_mul_f32 v[174:175], v[64:65], v[174:175]
	v_pk_mul_f32 v[176:177], v[66:67], v[176:177]
	v_cvt_pk_bf16_f32 v182, v174, v175
	v_cvt_pk_bf16_f32 v183, v176, v177
	global_store_dwordx2 v[162:163], v[182:183], off offset:96
	ds_write_b16 v150, v182 offset:7008
	ds_write_b16_d16_hi v150, v182 offset:7152
	ds_write_b16 v150, v183 offset:7296
	ds_write_b16_d16_hi v150, v183 offset:7440
	v_pk_mul_f32 v[174:175], v[60:61], v[60:61]
	v_pk_mul_f32 v[176:177], v[62:63], v[62:63]
	v_pk_fma_f32 v[174:175], v[174:175], v[170:171], v[168:169]
	v_pk_fma_f32 v[176:177], v[176:177], v[170:171], v[168:169]
	v_pk_mul_f32 v[174:175], v[60:61], v[174:175]
	v_pk_mul_f32 v[176:177], v[62:63], v[176:177]
	v_exp_f32_e32 v174, v174
	v_exp_f32_e32 v175, v175
	v_exp_f32_e32 v176, v176
	v_exp_f32_e32 v177, v177
	v_pk_add_f32 v[174:175], v[174:175], v[172:173]
	v_pk_add_f32 v[176:177], v[176:177], v[172:173]
	v_rcp_f32_e32 v174, v174
	v_rcp_f32_e32 v175, v175
	v_rcp_f32_e32 v176, v176
	v_rcp_f32_e32 v177, v177
	v_pk_mul_f32 v[174:175], v[60:61], v[174:175]
	v_pk_mul_f32 v[176:177], v[62:63], v[176:177]
	v_cvt_pk_bf16_f32 v178, v174, v175
	v_cvt_pk_bf16_f32 v179, v176, v177
	global_store_dwordx2 v[156:157], v[178:179], off offset:128
	ds_write_b16 v150, v178 offset:9216
	ds_write_b16_d16_hi v150, v178 offset:9360
	ds_write_b16 v150, v179 offset:9504
	ds_write_b16_d16_hi v150, v179 offset:9648
	v_pk_mul_f32 v[174:175], v[52:53], v[52:53]
	v_pk_mul_f32 v[176:177], v[54:55], v[54:55]
	v_pk_fma_f32 v[174:175], v[174:175], v[170:171], v[168:169]
	v_pk_fma_f32 v[176:177], v[176:177], v[170:171], v[168:169]
	v_pk_mul_f32 v[174:175], v[52:53], v[174:175]
	v_pk_mul_f32 v[176:177], v[54:55], v[176:177]
	v_exp_f32_e32 v174, v174
	v_exp_f32_e32 v175, v175
	v_exp_f32_e32 v176, v176
	v_exp_f32_e32 v177, v177
	v_pk_add_f32 v[174:175], v[174:175], v[172:173]
	v_pk_add_f32 v[176:177], v[176:177], v[172:173]
	v_rcp_f32_e32 v174, v174
	v_rcp_f32_e32 v175, v175
	v_rcp_f32_e32 v176, v176
	v_rcp_f32_e32 v177, v177
	v_pk_mul_f32 v[174:175], v[52:53], v[174:175]
	v_pk_mul_f32 v[176:177], v[54:55], v[176:177]
	v_cvt_pk_bf16_f32 v182, v174, v175
	v_cvt_pk_bf16_f32 v183, v176, v177
	global_store_dwordx2 v[158:159], v[182:183], off offset:128
	ds_write_b16 v150, v182 offset:9248
	ds_write_b16_d16_hi v150, v182 offset:9392
	ds_write_b16 v150, v183 offset:9536
	ds_write_b16_d16_hi v150, v183 offset:9680
	v_pk_mul_f32 v[174:175], v[56:57], v[56:57]
	v_pk_mul_f32 v[176:177], v[58:59], v[58:59]
	v_pk_fma_f32 v[174:175], v[174:175], v[170:171], v[168:169]
	v_pk_fma_f32 v[176:177], v[176:177], v[170:171], v[168:169]
	v_pk_mul_f32 v[174:175], v[56:57], v[174:175]
	v_pk_mul_f32 v[176:177], v[58:59], v[176:177]
	v_exp_f32_e32 v174, v174
	v_exp_f32_e32 v175, v175
	v_exp_f32_e32 v176, v176
	v_exp_f32_e32 v177, v177
	v_pk_add_f32 v[174:175], v[174:175], v[172:173]
	v_pk_add_f32 v[176:177], v[176:177], v[172:173]
	v_rcp_f32_e32 v174, v174
	v_rcp_f32_e32 v175, v175
	v_rcp_f32_e32 v176, v176
	v_rcp_f32_e32 v177, v177
	v_pk_mul_f32 v[174:175], v[56:57], v[174:175]
	v_pk_mul_f32 v[176:177], v[58:59], v[176:177]
	v_cvt_pk_bf16_f32 v178, v174, v175
	v_cvt_pk_bf16_f32 v179, v176, v177
	global_store_dwordx2 v[160:161], v[178:179], off offset:128
	ds_write_b16 v150, v178 offset:9280
	ds_write_b16_d16_hi v150, v178 offset:9424
	ds_write_b16 v150, v179 offset:9568
	ds_write_b16_d16_hi v150, v179 offset:9712
	v_pk_mul_f32 v[174:175], v[48:49], v[48:49]
	v_pk_mul_f32 v[176:177], v[50:51], v[50:51]
	v_pk_fma_f32 v[174:175], v[174:175], v[170:171], v[168:169]
	v_pk_fma_f32 v[176:177], v[176:177], v[170:171], v[168:169]
	v_pk_mul_f32 v[174:175], v[48:49], v[174:175]
	v_pk_mul_f32 v[176:177], v[50:51], v[176:177]
	v_exp_f32_e32 v174, v174
	v_exp_f32_e32 v175, v175
	v_exp_f32_e32 v176, v176
	v_exp_f32_e32 v177, v177
	v_pk_add_f32 v[174:175], v[174:175], v[172:173]
	v_pk_add_f32 v[176:177], v[176:177], v[172:173]
	v_rcp_f32_e32 v174, v174
	v_rcp_f32_e32 v175, v175
	v_rcp_f32_e32 v176, v176
	v_rcp_f32_e32 v177, v177
	v_pk_mul_f32 v[174:175], v[48:49], v[174:175]
	v_pk_mul_f32 v[176:177], v[50:51], v[176:177]
	v_cvt_pk_bf16_f32 v182, v174, v175
	v_cvt_pk_bf16_f32 v183, v176, v177
	global_store_dwordx2 v[162:163], v[182:183], off offset:128
	ds_write_b16 v150, v182 offset:9312
	ds_write_b16_d16_hi v150, v182 offset:9456
	ds_write_b16 v150, v183 offset:9600
	ds_write_b16_d16_hi v150, v183 offset:9744
	v_pk_mul_f32 v[174:175], v[44:45], v[44:45]
	v_pk_mul_f32 v[176:177], v[46:47], v[46:47]
	v_pk_fma_f32 v[174:175], v[174:175], v[170:171], v[168:169]
	v_pk_fma_f32 v[176:177], v[176:177], v[170:171], v[168:169]
	v_pk_mul_f32 v[174:175], v[44:45], v[174:175]
	v_pk_mul_f32 v[176:177], v[46:47], v[176:177]
	v_exp_f32_e32 v174, v174
	v_exp_f32_e32 v175, v175
	v_exp_f32_e32 v176, v176
	v_exp_f32_e32 v177, v177
	v_pk_add_f32 v[174:175], v[174:175], v[172:173]
	v_pk_add_f32 v[176:177], v[176:177], v[172:173]
	v_rcp_f32_e32 v174, v174
	v_rcp_f32_e32 v175, v175
	v_rcp_f32_e32 v176, v176
	v_rcp_f32_e32 v177, v177
	v_pk_mul_f32 v[174:175], v[44:45], v[174:175]
	v_pk_mul_f32 v[176:177], v[46:47], v[176:177]
	v_cvt_pk_bf16_f32 v178, v174, v175
	v_cvt_pk_bf16_f32 v179, v176, v177
	global_store_dwordx2 v[156:157], v[178:179], off offset:160
	ds_write_b16 v150, v178 offset:11520
	ds_write_b16_d16_hi v150, v178 offset:11664
	ds_write_b16 v150, v179 offset:11808
	ds_write_b16_d16_hi v150, v179 offset:11952
	v_pk_mul_f32 v[174:175], v[36:37], v[36:37]
	v_pk_mul_f32 v[176:177], v[38:39], v[38:39]
	v_pk_fma_f32 v[174:175], v[174:175], v[170:171], v[168:169]
	v_pk_fma_f32 v[176:177], v[176:177], v[170:171], v[168:169]
	v_pk_mul_f32 v[174:175], v[36:37], v[174:175]
	v_pk_mul_f32 v[176:177], v[38:39], v[176:177]
	v_exp_f32_e32 v174, v174
	v_exp_f32_e32 v175, v175
	v_exp_f32_e32 v176, v176
	v_exp_f32_e32 v177, v177
	v_pk_add_f32 v[174:175], v[174:175], v[172:173]
	v_pk_add_f32 v[176:177], v[176:177], v[172:173]
	v_rcp_f32_e32 v174, v174
	v_rcp_f32_e32 v175, v175
	v_rcp_f32_e32 v176, v176
	v_rcp_f32_e32 v177, v177
	v_pk_mul_f32 v[174:175], v[36:37], v[174:175]
	v_pk_mul_f32 v[176:177], v[38:39], v[176:177]
	v_cvt_pk_bf16_f32 v182, v174, v175
	v_cvt_pk_bf16_f32 v183, v176, v177
	global_store_dwordx2 v[158:159], v[182:183], off offset:160
	ds_write_b16 v150, v182 offset:11552
	ds_write_b16_d16_hi v150, v182 offset:11696
	ds_write_b16 v150, v183 offset:11840
	ds_write_b16_d16_hi v150, v183 offset:11984
	v_pk_mul_f32 v[174:175], v[40:41], v[40:41]
	v_pk_mul_f32 v[176:177], v[42:43], v[42:43]
	v_pk_fma_f32 v[174:175], v[174:175], v[170:171], v[168:169]
	v_pk_fma_f32 v[176:177], v[176:177], v[170:171], v[168:169]
	v_pk_mul_f32 v[174:175], v[40:41], v[174:175]
	v_pk_mul_f32 v[176:177], v[42:43], v[176:177]
	v_exp_f32_e32 v174, v174
	v_exp_f32_e32 v175, v175
	v_exp_f32_e32 v176, v176
	v_exp_f32_e32 v177, v177
	v_pk_add_f32 v[174:175], v[174:175], v[172:173]
	v_pk_add_f32 v[176:177], v[176:177], v[172:173]
	v_rcp_f32_e32 v174, v174
	v_rcp_f32_e32 v175, v175
	v_rcp_f32_e32 v176, v176
	v_rcp_f32_e32 v177, v177
	v_pk_mul_f32 v[174:175], v[40:41], v[174:175]
	v_pk_mul_f32 v[176:177], v[42:43], v[176:177]
	v_cvt_pk_bf16_f32 v178, v174, v175
	v_cvt_pk_bf16_f32 v179, v176, v177
	global_store_dwordx2 v[160:161], v[178:179], off offset:160
	ds_write_b16 v150, v178 offset:11584
	ds_write_b16_d16_hi v150, v178 offset:11728
	ds_write_b16 v150, v179 offset:11872
	ds_write_b16_d16_hi v150, v179 offset:12016
	v_pk_mul_f32 v[174:175], v[32:33], v[32:33]
	v_pk_mul_f32 v[176:177], v[34:35], v[34:35]
	v_pk_fma_f32 v[174:175], v[174:175], v[170:171], v[168:169]
	v_pk_fma_f32 v[176:177], v[176:177], v[170:171], v[168:169]
	v_pk_mul_f32 v[174:175], v[32:33], v[174:175]
	v_pk_mul_f32 v[176:177], v[34:35], v[176:177]
	v_exp_f32_e32 v174, v174
	v_exp_f32_e32 v175, v175
	v_exp_f32_e32 v176, v176
	v_exp_f32_e32 v177, v177
	v_pk_add_f32 v[174:175], v[174:175], v[172:173]
	v_pk_add_f32 v[176:177], v[176:177], v[172:173]
	v_rcp_f32_e32 v174, v174
	v_rcp_f32_e32 v175, v175
	v_rcp_f32_e32 v176, v176
	v_rcp_f32_e32 v177, v177
	v_pk_mul_f32 v[174:175], v[32:33], v[174:175]
	v_pk_mul_f32 v[176:177], v[34:35], v[176:177]
	v_cvt_pk_bf16_f32 v182, v174, v175
	v_cvt_pk_bf16_f32 v183, v176, v177
	global_store_dwordx2 v[162:163], v[182:183], off offset:160
	ds_write_b16 v150, v182 offset:11616
	ds_write_b16_d16_hi v150, v182 offset:11760
	ds_write_b16 v150, v183 offset:11904
	ds_write_b16_d16_hi v150, v183 offset:12048
	v_pk_mul_f32 v[174:175], v[28:29], v[28:29]
	v_pk_mul_f32 v[176:177], v[30:31], v[30:31]
	v_pk_fma_f32 v[174:175], v[174:175], v[170:171], v[168:169]
	v_pk_fma_f32 v[176:177], v[176:177], v[170:171], v[168:169]
	v_pk_mul_f32 v[174:175], v[28:29], v[174:175]
	v_pk_mul_f32 v[176:177], v[30:31], v[176:177]
	v_exp_f32_e32 v174, v174
	v_exp_f32_e32 v175, v175
	v_exp_f32_e32 v176, v176
	v_exp_f32_e32 v177, v177
	v_pk_add_f32 v[174:175], v[174:175], v[172:173]
	v_pk_add_f32 v[176:177], v[176:177], v[172:173]
	v_rcp_f32_e32 v174, v174
	v_rcp_f32_e32 v175, v175
	v_rcp_f32_e32 v176, v176
	v_rcp_f32_e32 v177, v177
	v_pk_mul_f32 v[174:175], v[28:29], v[174:175]
	v_pk_mul_f32 v[176:177], v[30:31], v[176:177]
	v_cvt_pk_bf16_f32 v178, v174, v175
	v_cvt_pk_bf16_f32 v179, v176, v177
	global_store_dwordx2 v[156:157], v[178:179], off offset:192
	ds_write_b16 v150, v178 offset:13824
	ds_write_b16_d16_hi v150, v178 offset:13968
	ds_write_b16 v150, v179 offset:14112
	ds_write_b16_d16_hi v150, v179 offset:14256
	v_pk_mul_f32 v[174:175], v[16:17], v[16:17]
	v_pk_mul_f32 v[176:177], v[18:19], v[18:19]
	v_pk_fma_f32 v[174:175], v[174:175], v[170:171], v[168:169]
	v_pk_fma_f32 v[176:177], v[176:177], v[170:171], v[168:169]
	v_pk_mul_f32 v[174:175], v[16:17], v[174:175]
	v_pk_mul_f32 v[176:177], v[18:19], v[176:177]
	v_exp_f32_e32 v174, v174
	v_exp_f32_e32 v175, v175
	v_exp_f32_e32 v176, v176
	v_exp_f32_e32 v177, v177
	v_pk_add_f32 v[174:175], v[174:175], v[172:173]
	v_pk_add_f32 v[176:177], v[176:177], v[172:173]
	v_rcp_f32_e32 v174, v174
	v_rcp_f32_e32 v175, v175
	v_rcp_f32_e32 v176, v176
	v_rcp_f32_e32 v177, v177
	v_pk_mul_f32 v[174:175], v[16:17], v[174:175]
	v_pk_mul_f32 v[176:177], v[18:19], v[176:177]
	v_cvt_pk_bf16_f32 v182, v174, v175
	v_cvt_pk_bf16_f32 v183, v176, v177
	global_store_dwordx2 v[158:159], v[182:183], off offset:192
	ds_write_b16 v150, v182 offset:13856
	ds_write_b16_d16_hi v150, v182 offset:14000
	ds_write_b16 v150, v183 offset:14144
	ds_write_b16_d16_hi v150, v183 offset:14288
	v_pk_mul_f32 v[174:175], v[24:25], v[24:25]
	v_pk_mul_f32 v[176:177], v[26:27], v[26:27]
	v_pk_fma_f32 v[174:175], v[174:175], v[170:171], v[168:169]
	v_pk_fma_f32 v[176:177], v[176:177], v[170:171], v[168:169]
	v_pk_mul_f32 v[174:175], v[24:25], v[174:175]
	v_pk_mul_f32 v[176:177], v[26:27], v[176:177]
	v_exp_f32_e32 v174, v174
	v_exp_f32_e32 v175, v175
	v_exp_f32_e32 v176, v176
	v_exp_f32_e32 v177, v177
	v_pk_add_f32 v[174:175], v[174:175], v[172:173]
	v_pk_add_f32 v[176:177], v[176:177], v[172:173]
	v_rcp_f32_e32 v174, v174
	v_rcp_f32_e32 v175, v175
	v_rcp_f32_e32 v176, v176
	v_rcp_f32_e32 v177, v177
	v_pk_mul_f32 v[174:175], v[24:25], v[174:175]
	v_pk_mul_f32 v[176:177], v[26:27], v[176:177]
	v_cvt_pk_bf16_f32 v178, v174, v175
	v_cvt_pk_bf16_f32 v179, v176, v177
	global_store_dwordx2 v[160:161], v[178:179], off offset:192
	ds_write_b16 v150, v178 offset:13888
	ds_write_b16_d16_hi v150, v178 offset:14032
	ds_write_b16 v150, v179 offset:14176
	ds_write_b16_d16_hi v150, v179 offset:14320
	v_pk_mul_f32 v[174:175], v[12:13], v[12:13]
	v_pk_mul_f32 v[176:177], v[14:15], v[14:15]
	v_pk_fma_f32 v[174:175], v[174:175], v[170:171], v[168:169]
	v_pk_fma_f32 v[176:177], v[176:177], v[170:171], v[168:169]
	v_pk_mul_f32 v[174:175], v[12:13], v[174:175]
	v_pk_mul_f32 v[176:177], v[14:15], v[176:177]
	v_exp_f32_e32 v174, v174
	v_exp_f32_e32 v175, v175
	v_exp_f32_e32 v176, v176
	v_exp_f32_e32 v177, v177
	v_pk_add_f32 v[174:175], v[174:175], v[172:173]
	v_pk_add_f32 v[176:177], v[176:177], v[172:173]
	v_rcp_f32_e32 v174, v174
	v_rcp_f32_e32 v175, v175
	v_rcp_f32_e32 v176, v176
	v_rcp_f32_e32 v177, v177
	v_pk_mul_f32 v[174:175], v[12:13], v[174:175]
	v_pk_mul_f32 v[176:177], v[14:15], v[176:177]
	v_cvt_pk_bf16_f32 v182, v174, v175
	v_cvt_pk_bf16_f32 v183, v176, v177
	global_store_dwordx2 v[162:163], v[182:183], off offset:192
	ds_write_b16 v150, v182 offset:13920
	ds_write_b16_d16_hi v150, v182 offset:14064
	ds_write_b16 v150, v183 offset:14208
	ds_write_b16_d16_hi v150, v183 offset:14352
	v_pk_mul_f32 v[174:175], v[4:5], v[4:5]
	v_pk_mul_f32 v[176:177], v[6:7], v[6:7]
	v_pk_fma_f32 v[174:175], v[174:175], v[170:171], v[168:169]
	v_pk_fma_f32 v[176:177], v[176:177], v[170:171], v[168:169]
	v_pk_mul_f32 v[174:175], v[4:5], v[174:175]
	v_pk_mul_f32 v[176:177], v[6:7], v[176:177]
	v_exp_f32_e32 v174, v174
	v_exp_f32_e32 v175, v175
	v_exp_f32_e32 v176, v176
	v_exp_f32_e32 v177, v177
	v_pk_add_f32 v[174:175], v[174:175], v[172:173]
	v_pk_add_f32 v[176:177], v[176:177], v[172:173]
	v_rcp_f32_e32 v174, v174
	v_rcp_f32_e32 v175, v175
	v_rcp_f32_e32 v176, v176
	v_rcp_f32_e32 v177, v177
	v_pk_mul_f32 v[174:175], v[4:5], v[174:175]
	v_pk_mul_f32 v[176:177], v[6:7], v[176:177]
	v_cvt_pk_bf16_f32 v178, v174, v175
	v_cvt_pk_bf16_f32 v179, v176, v177
	global_store_dwordx2 v[156:157], v[178:179], off offset:224
	ds_write_b16 v150, v178 offset:16128
	ds_write_b16_d16_hi v150, v178 offset:16272
	ds_write_b16 v150, v179 offset:16416
	ds_write_b16_d16_hi v150, v179 offset:16560
	v_pk_mul_f32 v[174:175], v[0:1], v[0:1]
	v_pk_mul_f32 v[176:177], v[2:3], v[2:3]
	v_pk_fma_f32 v[174:175], v[174:175], v[170:171], v[168:169]
	v_pk_fma_f32 v[176:177], v[176:177], v[170:171], v[168:169]
	v_pk_mul_f32 v[174:175], v[0:1], v[174:175]
	v_pk_mul_f32 v[176:177], v[2:3], v[176:177]
	v_exp_f32_e32 v174, v174
	v_exp_f32_e32 v175, v175
	v_exp_f32_e32 v176, v176
	v_exp_f32_e32 v177, v177
	v_pk_add_f32 v[174:175], v[174:175], v[172:173]
	v_pk_add_f32 v[176:177], v[176:177], v[172:173]
	v_rcp_f32_e32 v174, v174
	v_rcp_f32_e32 v175, v175
	v_rcp_f32_e32 v176, v176
	v_rcp_f32_e32 v177, v177
	v_pk_mul_f32 v[174:175], v[0:1], v[174:175]
	v_pk_mul_f32 v[176:177], v[2:3], v[176:177]
	v_cvt_pk_bf16_f32 v182, v174, v175
	v_cvt_pk_bf16_f32 v183, v176, v177
	global_store_dwordx2 v[158:159], v[182:183], off offset:224
	ds_write_b16 v150, v182 offset:16160
	ds_write_b16_d16_hi v150, v182 offset:16304
	ds_write_b16 v150, v183 offset:16448
	ds_write_b16_d16_hi v150, v183 offset:16592
	v_pk_mul_f32 v[174:175], v[20:21], v[20:21]
	v_pk_mul_f32 v[176:177], v[22:23], v[22:23]
	v_pk_fma_f32 v[174:175], v[174:175], v[170:171], v[168:169]
	v_pk_fma_f32 v[176:177], v[176:177], v[170:171], v[168:169]
	v_pk_mul_f32 v[174:175], v[20:21], v[174:175]
	v_pk_mul_f32 v[176:177], v[22:23], v[176:177]
	v_exp_f32_e32 v174, v174
	v_exp_f32_e32 v175, v175
	v_exp_f32_e32 v176, v176
	v_exp_f32_e32 v177, v177
	v_pk_add_f32 v[174:175], v[174:175], v[172:173]
	v_pk_add_f32 v[176:177], v[176:177], v[172:173]
	v_rcp_f32_e32 v174, v174
	v_rcp_f32_e32 v175, v175
	v_rcp_f32_e32 v176, v176
	v_rcp_f32_e32 v177, v177
	v_pk_mul_f32 v[174:175], v[20:21], v[174:175]
	v_pk_mul_f32 v[176:177], v[22:23], v[176:177]
	v_cvt_pk_bf16_f32 v178, v174, v175
	v_cvt_pk_bf16_f32 v179, v176, v177
	global_store_dwordx2 v[160:161], v[178:179], off offset:224
	ds_write_b16 v150, v178 offset:16192
	ds_write_b16_d16_hi v150, v178 offset:16336
	ds_write_b16 v150, v179 offset:16480
	ds_write_b16_d16_hi v150, v179 offset:16624
	v_pk_mul_f32 v[174:175], v[8:9], v[8:9]
	v_pk_mul_f32 v[176:177], v[10:11], v[10:11]
	v_pk_fma_f32 v[174:175], v[174:175], v[170:171], v[168:169]
	v_pk_fma_f32 v[176:177], v[176:177], v[170:171], v[168:169]
	v_pk_mul_f32 v[174:175], v[8:9], v[174:175]
	v_pk_mul_f32 v[176:177], v[10:11], v[176:177]
	v_exp_f32_e32 v174, v174
	v_exp_f32_e32 v175, v175
	v_exp_f32_e32 v176, v176
	v_exp_f32_e32 v177, v177
	v_pk_add_f32 v[174:175], v[174:175], v[172:173]
	v_pk_add_f32 v[176:177], v[176:177], v[172:173]
	v_rcp_f32_e32 v174, v174
	v_rcp_f32_e32 v175, v175
	v_rcp_f32_e32 v176, v176
	v_rcp_f32_e32 v177, v177
	v_pk_mul_f32 v[174:175], v[8:9], v[174:175]
	v_pk_mul_f32 v[176:177], v[10:11], v[176:177]
	v_cvt_pk_bf16_f32 v182, v174, v175
	v_cvt_pk_bf16_f32 v183, v176, v177
	global_store_dwordx2 v[162:163], v[182:183], off offset:224
	ds_write_b16 v150, v182 offset:16224
	ds_write_b16_d16_hi v150, v182 offset:16368
	ds_write_b16 v150, v183 offset:16512
	ds_write_b16_d16_hi v150, v183 offset:16656
	s_waitcnt lgkmcnt(0)
	ds_read_b128 v[184:187], v152
	ds_read_b128 v[188:191], v152 offset:1152
	ds_read_b128 v[192:195], v152 offset:2304
	ds_read_b128 v[196:199], v152 offset:3456
	ds_read_b128 v[200:203], v152 offset:4608
	ds_read_b128 v[204:207], v152 offset:5760
	ds_read_b128 v[208:211], v152 offset:6912
	ds_read_b128 v[212:215], v152 offset:8064
	s_waitcnt lgkmcnt(7)
	v_lshlrev_b32_e32 v134, 16, v184
	v_and_b32_e32 v135, 0xffff0000, v184
	v_lshlrev_b32_e32 v136, 16, v185
	v_and_b32_e32 v137, 0xffff0000, v185
	v_lshlrev_b32_e32 v138, 16, v186
	v_and_b32_e32 v139, 0xffff0000, v186
	v_lshlrev_b32_e32 v140, 16, v187
	v_and_b32_e32 v141, 0xffff0000, v187
	v_pk_mul_f32 v[142:143], v[134:135], v[134:135]
	v_pk_mul_f32 v[144:145], v[136:137], v[136:137]
	v_pk_mul_f32 v[248:249], v[138:139], v[138:139]
	v_pk_mul_f32 v[250:251], v[140:141], v[140:141]
	v_add_f32_e32 v184, v134, v135
	v_add_f32_e32 v185, v142, v143
	v_add_f32_e32 v158, v136, v137
	v_add_f32_e32 v159, v144, v145
	v_add_f32_e32 v160, v138, v139
	v_add_f32_e32 v161, v248, v249
	v_add_f32_e32 v162, v140, v141
	v_add_f32_e32 v163, v250, v251
	v_pk_add_f32 v[184:185], v[184:185], v[158:159]
	v_pk_add_f32 v[184:185], v[184:185], v[160:161]
	v_pk_add_f32 v[184:185], v[184:185], v[162:163]
	ds_read_b128 v[216:219], v152 offset:9216
	s_waitcnt lgkmcnt(7)
	v_lshlrev_b32_e32 v134, 16, v188
	v_and_b32_e32 v135, 0xffff0000, v188
	v_lshlrev_b32_e32 v136, 16, v189
	v_and_b32_e32 v137, 0xffff0000, v189
	v_lshlrev_b32_e32 v138, 16, v190
	v_and_b32_e32 v139, 0xffff0000, v190
	v_lshlrev_b32_e32 v140, 16, v191
	v_and_b32_e32 v141, 0xffff0000, v191
	v_pk_mul_f32 v[142:143], v[134:135], v[134:135]
	v_pk_mul_f32 v[144:145], v[136:137], v[136:137]
	v_pk_mul_f32 v[248:249], v[138:139], v[138:139]
	v_pk_mul_f32 v[250:251], v[140:141], v[140:141]
	v_add_f32_e32 v188, v134, v135
	v_add_f32_e32 v189, v142, v143
	v_add_f32_e32 v158, v136, v137
	v_add_f32_e32 v159, v144, v145
	v_add_f32_e32 v160, v138, v139
	v_add_f32_e32 v161, v248, v249
	v_add_f32_e32 v162, v140, v141
	v_add_f32_e32 v163, v250, v251
	v_pk_add_f32 v[188:189], v[188:189], v[158:159]
	v_pk_add_f32 v[188:189], v[188:189], v[160:161]
	v_pk_add_f32 v[188:189], v[188:189], v[162:163]
	ds_read_b128 v[220:223], v152 offset:10368
	s_nop 1
	v_add_f32_dpp v184, v184, v184 quad_perm:[1,0,3,2] row_mask:0xf bank_mask:0xf
	v_add_f32_dpp v185, v185, v185 quad_perm:[1,0,3,2] row_mask:0xf bank_mask:0xf
	v_add_f32_dpp v188, v188, v188 quad_perm:[1,0,3,2] row_mask:0xf bank_mask:0xf
	v_add_f32_dpp v189, v189, v189 quad_perm:[1,0,3,2] row_mask:0xf bank_mask:0xf
	v_add_f32_dpp v184, v184, v184 quad_perm:[2,3,0,1] row_mask:0xf bank_mask:0xf
	v_add_f32_dpp v185, v185, v185 quad_perm:[2,3,0,1] row_mask:0xf bank_mask:0xf
	v_add_f32_dpp v188, v188, v188 quad_perm:[2,3,0,1] row_mask:0xf bank_mask:0xf
	v_add_f32_dpp v189, v189, v189 quad_perm:[2,3,0,1] row_mask:0xf bank_mask:0xf
	v_add_f32_dpp v184, v184, v184 row_half_mirror row_mask:0xf bank_mask:0xf
	v_add_f32_dpp v185, v185, v185 row_half_mirror row_mask:0xf bank_mask:0xf
	v_add_f32_dpp v188, v188, v188 row_half_mirror row_mask:0xf bank_mask:0xf
	v_add_f32_dpp v189, v189, v189 row_half_mirror row_mask:0xf bank_mask:0xf
	s_waitcnt lgkmcnt(7)
	v_lshlrev_b32_e32 v134, 16, v192
	v_and_b32_e32 v135, 0xffff0000, v192
	v_lshlrev_b32_e32 v136, 16, v193
	v_and_b32_e32 v137, 0xffff0000, v193
	v_lshlrev_b32_e32 v138, 16, v194
	v_and_b32_e32 v139, 0xffff0000, v194
	v_lshlrev_b32_e32 v140, 16, v195
	v_and_b32_e32 v141, 0xffff0000, v195
	v_pk_mul_f32 v[142:143], v[134:135], v[134:135]
	v_pk_mul_f32 v[144:145], v[136:137], v[136:137]
	v_pk_mul_f32 v[248:249], v[138:139], v[138:139]
	v_pk_mul_f32 v[250:251], v[140:141], v[140:141]
	v_add_f32_e32 v192, v134, v135
	v_add_f32_e32 v193, v142, v143
	v_add_f32_e32 v158, v136, v137
	v_add_f32_e32 v159, v144, v145
	v_add_f32_e32 v160, v138, v139
	v_add_f32_e32 v161, v248, v249
	v_add_f32_e32 v162, v140, v141
	v_add_f32_e32 v163, v250, v251
	v_pk_add_f32 v[192:193], v[192:193], v[158:159]
	v_pk_add_f32 v[192:193], v[192:193], v[160:161]
	v_pk_add_f32 v[192:193], v[192:193], v[162:163]
	ds_read_b128 v[224:227], v152 offset:11520
	s_waitcnt lgkmcnt(7)
	v_lshlrev_b32_e32 v134, 16, v196
	v_and_b32_e32 v135, 0xffff0000, v196
	v_lshlrev_b32_e32 v136, 16, v197
	v_and_b32_e32 v137, 0xffff0000, v197
	v_lshlrev_b32_e32 v138, 16, v198
	v_and_b32_e32 v139, 0xffff0000, v198
	v_lshlrev_b32_e32 v140, 16, v199
	v_and_b32_e32 v141, 0xffff0000, v199
	v_pk_mul_f32 v[142:143], v[134:135], v[134:135]
	v_pk_mul_f32 v[144:145], v[136:137], v[136:137]
	v_pk_mul_f32 v[248:249], v[138:139], v[138:139]
	v_pk_mul_f32 v[250:251], v[140:141], v[140:141]
	v_add_f32_e32 v196, v134, v135
	v_add_f32_e32 v197, v142, v143
	v_add_f32_e32 v158, v136, v137
	v_add_f32_e32 v159, v144, v145
	v_add_f32_e32 v160, v138, v139
	v_add_f32_e32 v161, v248, v249
	v_add_f32_e32 v162, v140, v141
	v_add_f32_e32 v163, v250, v251
	v_pk_add_f32 v[196:197], v[196:197], v[158:159]
	v_pk_add_f32 v[196:197], v[196:197], v[160:161]
	v_pk_add_f32 v[196:197], v[196:197], v[162:163]
	ds_read_b128 v[228:231], v152 offset:12672
	s_nop 1
	v_add_f32_dpp v192, v192, v192 quad_perm:[1,0,3,2] row_mask:0xf bank_mask:0xf
	v_add_f32_dpp v193, v193, v193 quad_perm:[1,0,3,2] row_mask:0xf bank_mask:0xf
	v_add_f32_dpp v196, v196, v196 quad_perm:[1,0,3,2] row_mask:0xf bank_mask:0xf
	v_add_f32_dpp v197, v197, v197 quad_perm:[1,0,3,2] row_mask:0xf bank_mask:0xf
	v_add_f32_dpp v192, v192, v192 quad_perm:[2,3,0,1] row_mask:0xf bank_mask:0xf
	v_add_f32_dpp v193, v193, v193 quad_perm:[2,3,0,1] row_mask:0xf bank_mask:0xf
	v_add_f32_dpp v196, v196, v196 quad_perm:[2,3,0,1] row_mask:0xf bank_mask:0xf
	v_add_f32_dpp v197, v197, v197 quad_perm:[2,3,0,1] row_mask:0xf bank_mask:0xf
	v_add_f32_dpp v192, v192, v192 row_half_mirror row_mask:0xf bank_mask:0xf
	v_add_f32_dpp v193, v193, v193 row_half_mirror row_mask:0xf bank_mask:0xf
	v_add_f32_dpp v196, v196, v196 row_half_mirror row_mask:0xf bank_mask:0xf
	v_add_f32_dpp v197, v197, v197 row_half_mirror row_mask:0xf bank_mask:0xf
	s_waitcnt lgkmcnt(7)
	v_lshlrev_b32_e32 v134, 16, v200
	v_and_b32_e32 v135, 0xffff0000, v200
	v_lshlrev_b32_e32 v136, 16, v201
	v_and_b32_e32 v137, 0xffff0000, v201
	v_lshlrev_b32_e32 v138, 16, v202
	v_and_b32_e32 v139, 0xffff0000, v202
	v_lshlrev_b32_e32 v140, 16, v203
	v_and_b32_e32 v141, 0xffff0000, v203
	v_pk_mul_f32 v[142:143], v[134:135], v[134:135]
	v_pk_mul_f32 v[144:145], v[136:137], v[136:137]
	v_pk_mul_f32 v[248:249], v[138:139], v[138:139]
	v_pk_mul_f32 v[250:251], v[140:141], v[140:141]
	v_add_f32_e32 v200, v134, v135
	v_add_f32_e32 v201, v142, v143
	v_add_f32_e32 v158, v136, v137
	v_add_f32_e32 v159, v144, v145
	v_add_f32_e32 v160, v138, v139
	v_add_f32_e32 v161, v248, v249
	v_add_f32_e32 v162, v140, v141
	v_add_f32_e32 v163, v250, v251
	v_pk_add_f32 v[200:201], v[200:201], v[158:159]
	v_pk_add_f32 v[200:201], v[200:201], v[160:161]
	v_pk_add_f32 v[200:201], v[200:201], v[162:163]
	ds_read_b128 v[232:235], v152 offset:13824
	s_waitcnt lgkmcnt(7)
	v_lshlrev_b32_e32 v134, 16, v204
	v_and_b32_e32 v135, 0xffff0000, v204
	v_lshlrev_b32_e32 v136, 16, v205
	v_and_b32_e32 v137, 0xffff0000, v205
	v_lshlrev_b32_e32 v138, 16, v206
	v_and_b32_e32 v139, 0xffff0000, v206
	v_lshlrev_b32_e32 v140, 16, v207
	v_and_b32_e32 v141, 0xffff0000, v207
	v_pk_mul_f32 v[142:143], v[134:135], v[134:135]
	v_pk_mul_f32 v[144:145], v[136:137], v[136:137]
	v_pk_mul_f32 v[248:249], v[138:139], v[138:139]
	v_pk_mul_f32 v[250:251], v[140:141], v[140:141]
	v_add_f32_e32 v204, v134, v135
	v_add_f32_e32 v205, v142, v143
	v_add_f32_e32 v158, v136, v137
	v_add_f32_e32 v159, v144, v145
	v_add_f32_e32 v160, v138, v139
	v_add_f32_e32 v161, v248, v249
	v_add_f32_e32 v162, v140, v141
	v_add_f32_e32 v163, v250, v251
	v_pk_add_f32 v[204:205], v[204:205], v[158:159]
	v_pk_add_f32 v[204:205], v[204:205], v[160:161]
	v_pk_add_f32 v[204:205], v[204:205], v[162:163]
	ds_read_b128 v[236:239], v152 offset:14976
	s_nop 1
	v_add_f32_dpp v200, v200, v200 quad_perm:[1,0,3,2] row_mask:0xf bank_mask:0xf
	v_add_f32_dpp v201, v201, v201 quad_perm:[1,0,3,2] row_mask:0xf bank_mask:0xf
	v_add_f32_dpp v204, v204, v204 quad_perm:[1,0,3,2] row_mask:0xf bank_mask:0xf
	v_add_f32_dpp v205, v205, v205 quad_perm:[1,0,3,2] row_mask:0xf bank_mask:0xf
	v_add_f32_dpp v200, v200, v200 quad_perm:[2,3,0,1] row_mask:0xf bank_mask:0xf
	v_add_f32_dpp v201, v201, v201 quad_perm:[2,3,0,1] row_mask:0xf bank_mask:0xf
	v_add_f32_dpp v204, v204, v204 quad_perm:[2,3,0,1] row_mask:0xf bank_mask:0xf
	v_add_f32_dpp v205, v205, v205 quad_perm:[2,3,0,1] row_mask:0xf bank_mask:0xf
	v_add_f32_dpp v200, v200, v200 row_half_mirror row_mask:0xf bank_mask:0xf
	v_add_f32_dpp v201, v201, v201 row_half_mirror row_mask:0xf bank_mask:0xf
	v_add_f32_dpp v204, v204, v204 row_half_mirror row_mask:0xf bank_mask:0xf
	v_add_f32_dpp v205, v205, v205 row_half_mirror row_mask:0xf bank_mask:0xf
	s_waitcnt lgkmcnt(7)
	v_lshlrev_b32_e32 v134, 16, v208
	v_and_b32_e32 v135, 0xffff0000, v208
	v_lshlrev_b32_e32 v136, 16, v209
	v_and_b32_e32 v137, 0xffff0000, v209
	v_lshlrev_b32_e32 v138, 16, v210
	v_and_b32_e32 v139, 0xffff0000, v210
	v_lshlrev_b32_e32 v140, 16, v211
	v_and_b32_e32 v141, 0xffff0000, v211
	v_pk_mul_f32 v[142:143], v[134:135], v[134:135]
	v_pk_mul_f32 v[144:145], v[136:137], v[136:137]
	v_pk_mul_f32 v[248:249], v[138:139], v[138:139]
	v_pk_mul_f32 v[250:251], v[140:141], v[140:141]
	v_add_f32_e32 v208, v134, v135
	v_add_f32_e32 v209, v142, v143
	v_add_f32_e32 v158, v136, v137
	v_add_f32_e32 v159, v144, v145
	v_add_f32_e32 v160, v138, v139
	v_add_f32_e32 v161, v248, v249
	v_add_f32_e32 v162, v140, v141
	v_add_f32_e32 v163, v250, v251
	v_pk_add_f32 v[208:209], v[208:209], v[158:159]
	v_pk_add_f32 v[208:209], v[208:209], v[160:161]
	v_pk_add_f32 v[208:209], v[208:209], v[162:163]
	ds_read_b128 v[240:243], v152 offset:16128
	s_waitcnt lgkmcnt(7)
	v_lshlrev_b32_e32 v134, 16, v212
	v_and_b32_e32 v135, 0xffff0000, v212
	v_lshlrev_b32_e32 v136, 16, v213
	v_and_b32_e32 v137, 0xffff0000, v213
	v_lshlrev_b32_e32 v138, 16, v214
	v_and_b32_e32 v139, 0xffff0000, v214
	v_lshlrev_b32_e32 v140, 16, v215
	v_and_b32_e32 v141, 0xffff0000, v215
	v_pk_mul_f32 v[142:143], v[134:135], v[134:135]
	v_pk_mul_f32 v[144:145], v[136:137], v[136:137]
	v_pk_mul_f32 v[248:249], v[138:139], v[138:139]
	v_pk_mul_f32 v[250:251], v[140:141], v[140:141]
	v_add_f32_e32 v212, v134, v135
	v_add_f32_e32 v213, v142, v143
	v_add_f32_e32 v158, v136, v137
	v_add_f32_e32 v159, v144, v145
	v_add_f32_e32 v160, v138, v139
	v_add_f32_e32 v161, v248, v249
	v_add_f32_e32 v162, v140, v141
	v_add_f32_e32 v163, v250, v251
	v_pk_add_f32 v[212:213], v[212:213], v[158:159]
	v_pk_add_f32 v[212:213], v[212:213], v[160:161]
	v_pk_add_f32 v[212:213], v[212:213], v[162:163]
	ds_read_b128 v[244:247], v152 offset:17280
	s_nop 1
	v_add_f32_dpp v208, v208, v208 quad_perm:[1,0,3,2] row_mask:0xf bank_mask:0xf
	v_add_f32_dpp v209, v209, v209 quad_perm:[1,0,3,2] row_mask:0xf bank_mask:0xf
	v_add_f32_dpp v212, v212, v212 quad_perm:[1,0,3,2] row_mask:0xf bank_mask:0xf
	v_add_f32_dpp v213, v213, v213 quad_perm:[1,0,3,2] row_mask:0xf bank_mask:0xf
	v_add_f32_dpp v208, v208, v208 quad_perm:[2,3,0,1] row_mask:0xf bank_mask:0xf
	v_add_f32_dpp v209, v209, v209 quad_perm:[2,3,0,1] row_mask:0xf bank_mask:0xf
	v_add_f32_dpp v212, v212, v212 quad_perm:[2,3,0,1] row_mask:0xf bank_mask:0xf
	v_add_f32_dpp v213, v213, v213 quad_perm:[2,3,0,1] row_mask:0xf bank_mask:0xf
	v_add_f32_dpp v208, v208, v208 row_half_mirror row_mask:0xf bank_mask:0xf
	v_add_f32_dpp v209, v209, v209 row_half_mirror row_mask:0xf bank_mask:0xf
	v_add_f32_dpp v212, v212, v212 row_half_mirror row_mask:0xf bank_mask:0xf
	v_add_f32_dpp v213, v213, v213 row_half_mirror row_mask:0xf bank_mask:0xf
	s_waitcnt lgkmcnt(7)
	v_lshlrev_b32_e32 v134, 16, v216
	v_and_b32_e32 v135, 0xffff0000, v216
	v_lshlrev_b32_e32 v136, 16, v217
	v_and_b32_e32 v137, 0xffff0000, v217
	v_lshlrev_b32_e32 v138, 16, v218
	v_and_b32_e32 v139, 0xffff0000, v218
	v_lshlrev_b32_e32 v140, 16, v219
	v_and_b32_e32 v141, 0xffff0000, v219
	v_pk_mul_f32 v[142:143], v[134:135], v[134:135]
	v_pk_mul_f32 v[144:145], v[136:137], v[136:137]
	v_pk_mul_f32 v[248:249], v[138:139], v[138:139]
	v_pk_mul_f32 v[250:251], v[140:141], v[140:141]
	v_add_f32_e32 v216, v134, v135
	v_add_f32_e32 v217, v142, v143
	v_add_f32_e32 v158, v136, v137
	v_add_f32_e32 v159, v144, v145
	v_add_f32_e32 v160, v138, v139
	v_add_f32_e32 v161, v248, v249
	v_add_f32_e32 v162, v140, v141
	v_add_f32_e32 v163, v250, v251
	v_pk_add_f32 v[216:217], v[216:217], v[158:159]
	v_pk_add_f32 v[216:217], v[216:217], v[160:161]
	v_pk_add_f32 v[216:217], v[216:217], v[162:163]
	s_waitcnt lgkmcnt(6)
	v_lshlrev_b32_e32 v134, 16, v220
	v_and_b32_e32 v135, 0xffff0000, v220
	v_lshlrev_b32_e32 v136, 16, v221
	v_and_b32_e32 v137, 0xffff0000, v221
	v_lshlrev_b32_e32 v138, 16, v222
	v_and_b32_e32 v139, 0xffff0000, v222
	v_lshlrev_b32_e32 v140, 16, v223
	v_and_b32_e32 v141, 0xffff0000, v223
	v_pk_mul_f32 v[142:143], v[134:135], v[134:135]
	v_pk_mul_f32 v[144:145], v[136:137], v[136:137]
	v_pk_mul_f32 v[248:249], v[138:139], v[138:139]
	v_pk_mul_f32 v[250:251], v[140:141], v[140:141]
	v_add_f32_e32 v220, v134, v135
	v_add_f32_e32 v221, v142, v143
	v_add_f32_e32 v158, v136, v137
	v_add_f32_e32 v159, v144, v145
	v_add_f32_e32 v160, v138, v139
	v_add_f32_e32 v161, v248, v249
	v_add_f32_e32 v162, v140, v141
	v_add_f32_e32 v163, v250, v251
	v_pk_add_f32 v[220:221], v[220:221], v[158:159]
	v_pk_add_f32 v[220:221], v[220:221], v[160:161]
	v_pk_add_f32 v[220:221], v[220:221], v[162:163]
	s_nop 1
	v_add_f32_dpp v216, v216, v216 quad_perm:[1,0,3,2] row_mask:0xf bank_mask:0xf
	v_add_f32_dpp v217, v217, v217 quad_perm:[1,0,3,2] row_mask:0xf bank_mask:0xf
	v_add_f32_dpp v220, v220, v220 quad_perm:[1,0,3,2] row_mask:0xf bank_mask:0xf
	v_add_f32_dpp v221, v221, v221 quad_perm:[1,0,3,2] row_mask:0xf bank_mask:0xf
	v_add_f32_dpp v216, v216, v216 quad_perm:[2,3,0,1] row_mask:0xf bank_mask:0xf
	v_add_f32_dpp v217, v217, v217 quad_perm:[2,3,0,1] row_mask:0xf bank_mask:0xf
	v_add_f32_dpp v220, v220, v220 quad_perm:[2,3,0,1] row_mask:0xf bank_mask:0xf
	v_add_f32_dpp v221, v221, v221 quad_perm:[2,3,0,1] row_mask:0xf bank_mask:0xf
	v_add_f32_dpp v216, v216, v216 row_half_mirror row_mask:0xf bank_mask:0xf
	v_add_f32_dpp v217, v217, v217 row_half_mirror row_mask:0xf bank_mask:0xf
	v_add_f32_dpp v220, v220, v220 row_half_mirror row_mask:0xf bank_mask:0xf
	v_add_f32_dpp v221, v221, v221 row_half_mirror row_mask:0xf bank_mask:0xf
	s_waitcnt lgkmcnt(5)
	v_lshlrev_b32_e32 v134, 16, v224
	v_and_b32_e32 v135, 0xffff0000, v224
	v_lshlrev_b32_e32 v136, 16, v225
	v_and_b32_e32 v137, 0xffff0000, v225
	v_lshlrev_b32_e32 v138, 16, v226
	v_and_b32_e32 v139, 0xffff0000, v226
	v_lshlrev_b32_e32 v140, 16, v227
	v_and_b32_e32 v141, 0xffff0000, v227
	v_pk_mul_f32 v[142:143], v[134:135], v[134:135]
	v_pk_mul_f32 v[144:145], v[136:137], v[136:137]
	v_pk_mul_f32 v[248:249], v[138:139], v[138:139]
	v_pk_mul_f32 v[250:251], v[140:141], v[140:141]
	v_add_f32_e32 v224, v134, v135
	v_add_f32_e32 v225, v142, v143
	v_add_f32_e32 v158, v136, v137
	v_add_f32_e32 v159, v144, v145
	v_add_f32_e32 v160, v138, v139
	v_add_f32_e32 v161, v248, v249
	v_add_f32_e32 v162, v140, v141
	v_add_f32_e32 v163, v250, v251
	v_pk_add_f32 v[224:225], v[224:225], v[158:159]
	v_pk_add_f32 v[224:225], v[224:225], v[160:161]
	v_pk_add_f32 v[224:225], v[224:225], v[162:163]
	s_waitcnt lgkmcnt(4)
	v_lshlrev_b32_e32 v134, 16, v228
	v_and_b32_e32 v135, 0xffff0000, v228
	v_lshlrev_b32_e32 v136, 16, v229
	v_and_b32_e32 v137, 0xffff0000, v229
	v_lshlrev_b32_e32 v138, 16, v230
	v_and_b32_e32 v139, 0xffff0000, v230
	v_lshlrev_b32_e32 v140, 16, v231
	v_and_b32_e32 v141, 0xffff0000, v231
	v_pk_mul_f32 v[142:143], v[134:135], v[134:135]
	v_pk_mul_f32 v[144:145], v[136:137], v[136:137]
	v_pk_mul_f32 v[248:249], v[138:139], v[138:139]
	v_pk_mul_f32 v[250:251], v[140:141], v[140:141]
	v_add_f32_e32 v228, v134, v135
	v_add_f32_e32 v229, v142, v143
	v_add_f32_e32 v158, v136, v137
	v_add_f32_e32 v159, v144, v145
	v_add_f32_e32 v160, v138, v139
	v_add_f32_e32 v161, v248, v249
	v_add_f32_e32 v162, v140, v141
	v_add_f32_e32 v163, v250, v251
	v_pk_add_f32 v[228:229], v[228:229], v[158:159]
	v_pk_add_f32 v[228:229], v[228:229], v[160:161]
	v_pk_add_f32 v[228:229], v[228:229], v[162:163]
	s_nop 1
	v_add_f32_dpp v224, v224, v224 quad_perm:[1,0,3,2] row_mask:0xf bank_mask:0xf
	v_add_f32_dpp v225, v225, v225 quad_perm:[1,0,3,2] row_mask:0xf bank_mask:0xf
	v_add_f32_dpp v228, v228, v228 quad_perm:[1,0,3,2] row_mask:0xf bank_mask:0xf
	v_add_f32_dpp v229, v229, v229 quad_perm:[1,0,3,2] row_mask:0xf bank_mask:0xf
	v_add_f32_dpp v224, v224, v224 quad_perm:[2,3,0,1] row_mask:0xf bank_mask:0xf
	v_add_f32_dpp v225, v225, v225 quad_perm:[2,3,0,1] row_mask:0xf bank_mask:0xf
	v_add_f32_dpp v228, v228, v228 quad_perm:[2,3,0,1] row_mask:0xf bank_mask:0xf
	v_add_f32_dpp v229, v229, v229 quad_perm:[2,3,0,1] row_mask:0xf bank_mask:0xf
	v_add_f32_dpp v224, v224, v224 row_half_mirror row_mask:0xf bank_mask:0xf
	v_add_f32_dpp v225, v225, v225 row_half_mirror row_mask:0xf bank_mask:0xf
	v_add_f32_dpp v228, v228, v228 row_half_mirror row_mask:0xf bank_mask:0xf
	v_add_f32_dpp v229, v229, v229 row_half_mirror row_mask:0xf bank_mask:0xf
	s_waitcnt lgkmcnt(3)
	v_lshlrev_b32_e32 v134, 16, v232
	v_and_b32_e32 v135, 0xffff0000, v232
	v_lshlrev_b32_e32 v136, 16, v233
	v_and_b32_e32 v137, 0xffff0000, v233
	v_lshlrev_b32_e32 v138, 16, v234
	v_and_b32_e32 v139, 0xffff0000, v234
	v_lshlrev_b32_e32 v140, 16, v235
	v_and_b32_e32 v141, 0xffff0000, v235
	v_pk_mul_f32 v[142:143], v[134:135], v[134:135]
	v_pk_mul_f32 v[144:145], v[136:137], v[136:137]
	v_pk_mul_f32 v[248:249], v[138:139], v[138:139]
	v_pk_mul_f32 v[250:251], v[140:141], v[140:141]
	v_add_f32_e32 v232, v134, v135
	v_add_f32_e32 v233, v142, v143
	v_add_f32_e32 v158, v136, v137
	v_add_f32_e32 v159, v144, v145
	v_add_f32_e32 v160, v138, v139
	v_add_f32_e32 v161, v248, v249
	v_add_f32_e32 v162, v140, v141
	v_add_f32_e32 v163, v250, v251
	v_pk_add_f32 v[232:233], v[232:233], v[158:159]
	v_pk_add_f32 v[232:233], v[232:233], v[160:161]
	v_pk_add_f32 v[232:233], v[232:233], v[162:163]
	s_waitcnt lgkmcnt(2)
	v_lshlrev_b32_e32 v134, 16, v236
	v_and_b32_e32 v135, 0xffff0000, v236
	v_lshlrev_b32_e32 v136, 16, v237
	v_and_b32_e32 v137, 0xffff0000, v237
	v_lshlrev_b32_e32 v138, 16, v238
	v_and_b32_e32 v139, 0xffff0000, v238
	v_lshlrev_b32_e32 v140, 16, v239
	v_and_b32_e32 v141, 0xffff0000, v239
	v_pk_mul_f32 v[142:143], v[134:135], v[134:135]
	v_pk_mul_f32 v[144:145], v[136:137], v[136:137]
	v_pk_mul_f32 v[248:249], v[138:139], v[138:139]
	v_pk_mul_f32 v[250:251], v[140:141], v[140:141]
	v_add_f32_e32 v236, v134, v135
	v_add_f32_e32 v237, v142, v143
	v_add_f32_e32 v158, v136, v137
	v_add_f32_e32 v159, v144, v145
	v_add_f32_e32 v160, v138, v139
	v_add_f32_e32 v161, v248, v249
	v_add_f32_e32 v162, v140, v141
	v_add_f32_e32 v163, v250, v251
	v_pk_add_f32 v[236:237], v[236:237], v[158:159]
	v_pk_add_f32 v[236:237], v[236:237], v[160:161]
	v_pk_add_f32 v[236:237], v[236:237], v[162:163]
	s_nop 1
	v_add_f32_dpp v232, v232, v232 quad_perm:[1,0,3,2] row_mask:0xf bank_mask:0xf
	v_add_f32_dpp v233, v233, v233 quad_perm:[1,0,3,2] row_mask:0xf bank_mask:0xf
	v_add_f32_dpp v236, v236, v236 quad_perm:[1,0,3,2] row_mask:0xf bank_mask:0xf
	v_add_f32_dpp v237, v237, v237 quad_perm:[1,0,3,2] row_mask:0xf bank_mask:0xf
	v_add_f32_dpp v232, v232, v232 quad_perm:[2,3,0,1] row_mask:0xf bank_mask:0xf
	v_add_f32_dpp v233, v233, v233 quad_perm:[2,3,0,1] row_mask:0xf bank_mask:0xf
	v_add_f32_dpp v236, v236, v236 quad_perm:[2,3,0,1] row_mask:0xf bank_mask:0xf
	v_add_f32_dpp v237, v237, v237 quad_perm:[2,3,0,1] row_mask:0xf bank_mask:0xf
	v_add_f32_dpp v232, v232, v232 row_half_mirror row_mask:0xf bank_mask:0xf
	v_add_f32_dpp v233, v233, v233 row_half_mirror row_mask:0xf bank_mask:0xf
	v_add_f32_dpp v236, v236, v236 row_half_mirror row_mask:0xf bank_mask:0xf
	v_add_f32_dpp v237, v237, v237 row_half_mirror row_mask:0xf bank_mask:0xf
	s_waitcnt lgkmcnt(1)
	v_lshlrev_b32_e32 v134, 16, v240
	v_and_b32_e32 v135, 0xffff0000, v240
	v_lshlrev_b32_e32 v136, 16, v241
	v_and_b32_e32 v137, 0xffff0000, v241
	v_lshlrev_b32_e32 v138, 16, v242
	v_and_b32_e32 v139, 0xffff0000, v242
	v_lshlrev_b32_e32 v140, 16, v243
	v_and_b32_e32 v141, 0xffff0000, v243
	v_pk_mul_f32 v[142:143], v[134:135], v[134:135]
	v_pk_mul_f32 v[144:145], v[136:137], v[136:137]
	v_pk_mul_f32 v[248:249], v[138:139], v[138:139]
	v_pk_mul_f32 v[250:251], v[140:141], v[140:141]
	v_add_f32_e32 v240, v134, v135
	v_add_f32_e32 v241, v142, v143
	v_add_f32_e32 v158, v136, v137
	v_add_f32_e32 v159, v144, v145
	v_add_f32_e32 v160, v138, v139
	v_add_f32_e32 v161, v248, v249
	v_add_f32_e32 v162, v140, v141
	v_add_f32_e32 v163, v250, v251
	v_pk_add_f32 v[240:241], v[240:241], v[158:159]
	v_pk_add_f32 v[240:241], v[240:241], v[160:161]
	v_pk_add_f32 v[240:241], v[240:241], v[162:163]
	s_waitcnt lgkmcnt(0)
	v_lshlrev_b32_e32 v134, 16, v244
	v_and_b32_e32 v135, 0xffff0000, v244
	v_lshlrev_b32_e32 v136, 16, v245
	v_and_b32_e32 v137, 0xffff0000, v245
	v_lshlrev_b32_e32 v138, 16, v246
	v_and_b32_e32 v139, 0xffff0000, v246
	v_lshlrev_b32_e32 v140, 16, v247
	v_and_b32_e32 v141, 0xffff0000, v247
	v_pk_mul_f32 v[142:143], v[134:135], v[134:135]
	v_pk_mul_f32 v[144:145], v[136:137], v[136:137]
	v_pk_mul_f32 v[248:249], v[138:139], v[138:139]
	v_pk_mul_f32 v[250:251], v[140:141], v[140:141]
	v_add_f32_e32 v244, v134, v135
	v_add_f32_e32 v245, v142, v143
	v_add_f32_e32 v158, v136, v137
	v_add_f32_e32 v159, v144, v145
	v_add_f32_e32 v160, v138, v139
	v_add_f32_e32 v161, v248, v249
	v_add_f32_e32 v162, v140, v141
	v_add_f32_e32 v163, v250, v251
	v_pk_add_f32 v[244:245], v[244:245], v[158:159]
	v_pk_add_f32 v[244:245], v[244:245], v[160:161]
	v_pk_add_f32 v[244:245], v[244:245], v[162:163]
	s_nop 1
	v_add_f32_dpp v240, v240, v240 quad_perm:[1,0,3,2] row_mask:0xf bank_mask:0xf
	v_add_f32_dpp v241, v241, v241 quad_perm:[1,0,3,2] row_mask:0xf bank_mask:0xf
	v_add_f32_dpp v244, v244, v244 quad_perm:[1,0,3,2] row_mask:0xf bank_mask:0xf
	v_add_f32_dpp v245, v245, v245 quad_perm:[1,0,3,2] row_mask:0xf bank_mask:0xf
	v_add_f32_dpp v240, v240, v240 quad_perm:[2,3,0,1] row_mask:0xf bank_mask:0xf
	v_add_f32_dpp v241, v241, v241 quad_perm:[2,3,0,1] row_mask:0xf bank_mask:0xf
	v_add_f32_dpp v244, v244, v244 quad_perm:[2,3,0,1] row_mask:0xf bank_mask:0xf
	v_add_f32_dpp v245, v245, v245 quad_perm:[2,3,0,1] row_mask:0xf bank_mask:0xf
	v_add_f32_dpp v240, v240, v240 row_half_mirror row_mask:0xf bank_mask:0xf
	v_add_f32_dpp v241, v241, v241 row_half_mirror row_mask:0xf bank_mask:0xf
	v_add_f32_dpp v244, v244, v244 row_half_mirror row_mask:0xf bank_mask:0xf
	v_add_f32_dpp v245, v245, v245 row_half_mirror row_mask:0xf bank_mask:0xf
	s_and_saveexec_b64 s[60:61], s[4:5]
	global_store_dwordx2 v129, v[184:185], s[8:9]
	v_add_u32_e32 v129, 0x800, v129
	global_store_dwordx2 v129, v[188:189], s[8:9]
	v_add_u32_e32 v129, 0x800, v129
	global_store_dwordx2 v129, v[192:193], s[8:9]
	v_add_u32_e32 v129, 0x800, v129
	global_store_dwordx2 v129, v[196:197], s[8:9]
	v_add_u32_e32 v129, 0x800, v129
	global_store_dwordx2 v129, v[200:201], s[8:9]
	v_add_u32_e32 v129, 0x800, v129
	global_store_dwordx2 v129, v[204:205], s[8:9]
	v_add_u32_e32 v129, 0x800, v129
	global_store_dwordx2 v129, v[208:209], s[8:9]
	v_add_u32_e32 v129, 0x800, v129
	global_store_dwordx2 v129, v[212:213], s[8:9]
	v_add_u32_e32 v129, 0x800, v129
	global_store_dwordx2 v129, v[216:217], s[8:9]
	v_add_u32_e32 v129, 0x800, v129
	global_store_dwordx2 v129, v[220:221], s[8:9]
	v_add_u32_e32 v129, 0x800, v129
	global_store_dwordx2 v129, v[224:225], s[8:9]
	v_add_u32_e32 v129, 0x800, v129
	global_store_dwordx2 v129, v[228:229], s[8:9]
	v_add_u32_e32 v129, 0x800, v129
	global_store_dwordx2 v129, v[232:233], s[8:9]
	v_add_u32_e32 v129, 0x800, v129
	global_store_dwordx2 v129, v[236:237], s[8:9]
	v_add_u32_e32 v129, 0x800, v129
	global_store_dwordx2 v129, v[240:241], s[8:9]
	v_add_u32_e32 v129, 0x800, v129
	global_store_dwordx2 v129, v[244:245], s[8:9]
	s_or_b64 exec, exec, s[60:61]
	s_waitcnt lgkmcnt(0)

.LBB0_1494:
	v_lshl_add_u32 v136, s42, 2, v147
	v_mul_f32_e32 v129, 0x3d372713, v124
	v_mul_f32_e32 v134, 0x3d372713, v125
	v_mul_f32_e32 v137, 0x3d372713, v126
	v_mul_f32_e32 v138, 0x3d372713, v127
	v_mul_f32_e32 v139, 0x3d372713, v116
	v_mul_f32_e32 v142, 0x3d372713, v117
	v_mul_f32_e32 v145, 0x3d372713, v118
	v_mul_f32_e32 v155, 0x3d372713, v119
	v_mul_f32_e32 v156, 0x3d372713, v108
	v_mul_f32_e32 v157, 0x3d372713, v109
	v_mul_f32_e32 v158, 0x3d372713, v110
	v_mul_f32_e32 v159, 0x3d372713, v111
	v_mul_f32_e32 v160, 0x3d372713, v100
	v_mul_f32_e32 v161, 0x3d372713, v101
	v_mul_f32_e32 v162, 0x3d372713, v102
	v_mul_f32_e32 v169, 0x3d372713, v103
	v_mul_f32_e32 v170, 0x3d372713, v92
	v_mul_f32_e32 v171, 0x3d372713, v93
	v_mul_f32_e32 v172, 0x3d372713, v94
	v_mul_f32_e32 v173, 0x3d372713, v95
	s_lshl_b32 s46, s56, 8
	v_cmp_lt_i32_e32 vcc, 63, v136
	v_mul_f32_e32 v135, v124, v129
	v_mul_f32_e32 v144, v125, v134
	v_mul_f32_e32 v141, v126, v137
	v_mul_f32_e32 v140, v127, v138
	v_mul_f32_e32 v143, v116, v139
	v_mul_f32_e32 v142, v117, v142
	v_mul_f32_e32 v139, v118, v145
	v_mul_f32_e32 v138, v119, v155
	v_mul_f32_e32 v168, v108, v156
	v_mul_f32_e32 v167, v109, v157
	v_mul_f32_e32 v166, v110, v158
	v_mul_f32_e32 v165, v111, v159
	v_mul_f32_e32 v164, v100, v160
	v_mul_f32_e32 v163, v101, v161
	v_mul_f32_e32 v162, v102, v162
	v_mul_f32_e32 v161, v103, v169
	v_mul_f32_e32 v160, v92, v170
	v_mul_f32_e32 v159, v93, v171
	v_mul_f32_e32 v158, v94, v172
	v_mul_f32_e32 v157, v95, v173
	v_mul_f32_e32 v156, 0x3d372713, v84
	v_mul_f32_e32 v155, 0x3d372713, v85
	v_mul_f32_e32 v137, 0x3d372713, v86
	v_mul_f32_e32 v129, 0x3d372713, v87
	s_and_saveexec_b64 s[20:21], vcc
	s_xor_b64 s[42:43], exec, s[20:21]
	s_cbranch_execz .LBB0_1502
	v_subrev_u32_e32 v136, 64, v136
	v_add_u32_e32 v129, s46, v151
	v_lshlrev_b32_e32 v129, 8, v129
	v_lshl_add_u32 v129, v136, 3, v129
	v_lshl_add_u32 v164, s53, 1, v146
	v_ashrrev_i32_e32 v165, 31, v164
	v_lshlrev_b64 v[164:165], 19, v[164:165]
	v_lshl_add_u64 v[164:165], v[130:131], 0, v[164:165]
	v_lshl_or_b32 v166, v136, 6, v148
	v_mov_b32_e32 v167, 0
	v_lshlrev_b64 v[166:167], 8, v[166:167]
	v_lshl_add_u64 v[156:157], v[164:165], 0, v[166:167]
	s_mov_b64 s[44:45], 0x1000
	v_lshl_add_u64 v[158:159], v[156:157], 0, s[44:45]
	v_lshl_add_u64 v[160:161], v[158:159], 0, s[44:45]
	v_lshl_add_u64 v[162:163], v[160:161], 0, s[44:45]
	v_mov_b32_e32 v168, 0xc0135761
	v_mov_b32_e32 v169, 0xc0135761
	v_mov_b32_e32 v170, 0xbdd2d3e7
	v_mov_b32_e32 v171, 0xbdd2d3e7
	v_mov_b32_e32 v172, 0x3f800000
	v_mov_b32_e32 v173, 0x3f800000
	v_pk_mul_f32 v[174:175], v[124:125], v[124:125]
	v_pk_mul_f32 v[176:177], v[126:127], v[126:127]
	v_pk_fma_f32 v[174:175], v[174:175], v[170:171], v[168:169]
	v_pk_fma_f32 v[176:177], v[176:177], v[170:171], v[168:169]
	v_pk_mul_f32 v[174:175], v[124:125], v[174:175]
	v_pk_mul_f32 v[176:177], v[126:127], v[176:177]
	v_exp_f32_e32 v174, v174
	v_exp_f32_e32 v175, v175
	v_exp_f32_e32 v176, v176
	v_exp_f32_e32 v177, v177
	v_pk_add_f32 v[174:175], v[174:175], v[172:173]
	v_pk_add_f32 v[176:177], v[176:177], v[172:173]
	v_rcp_f32_e32 v174, v174
	v_rcp_f32_e32 v175, v175
	v_rcp_f32_e32 v176, v176
	v_rcp_f32_e32 v177, v177
	v_pk_mul_f32 v[174:175], v[124:125], v[174:175]
	v_pk_mul_f32 v[176:177], v[126:127], v[176:177]
	v_cvt_pk_bf16_f32 v178, v174, v175
	v_cvt_pk_bf16_f32 v179, v176, v177
	global_store_dwordx2 v[156:157], v[178:179], off
	ds_write_b16 v150, v178
	ds_write_b16_d16_hi v150, v178 offset:144
	ds_write_b16 v150, v179 offset:288
	ds_write_b16_d16_hi v150, v179 offset:432
	v_pk_mul_f32 v[174:175], v[116:117], v[116:117]
	v_pk_mul_f32 v[176:177], v[118:119], v[118:119]
	v_pk_fma_f32 v[174:175], v[174:175], v[170:171], v[168:169]
	v_pk_fma_f32 v[176:177], v[176:177], v[170:171], v[168:169]
	v_pk_mul_f32 v[174:175], v[116:117], v[174:175]
	v_pk_mul_f32 v[176:177], v[118:119], v[176:177]
	v_exp_f32_e32 v174, v174
	v_exp_f32_e32 v175, v175
	v_exp_f32_e32 v176, v176
	v_exp_f32_e32 v177, v177
	v_pk_add_f32 v[174:175], v[174:175], v[172:173]
	v_pk_add_f32 v[176:177], v[176:177], v[172:173]
	v_rcp_f32_e32 v174, v174
	v_rcp_f32_e32 v175, v175
	v_rcp_f32_e32 v176, v176
	v_rcp_f32_e32 v177, v177
	v_pk_mul_f32 v[174:175], v[116:117], v[174:175]
	v_pk_mul_f32 v[176:177], v[118:119], v[176:177]
	v_cvt_pk_bf16_f32 v182, v174, v175
	v_cvt_pk_bf16_f32 v183, v176, v177
	global_store_dwordx2 v[158:159], v[182:183], off
	ds_write_b16 v150, v182 offset:32
	ds_write_b16_d16_hi v150, v182 offset:176
	ds_write_b16 v150, v183 offset:320
	ds_write_b16_d16_hi v150, v183 offset:464
	v_pk_mul_f32 v[174:175], v[120:121], v[120:121]
	v_pk_mul_f32 v[176:177], v[122:123], v[122:123]
	v_pk_fma_f32 v[174:175], v[174:175], v[170:171], v[168:169]
	v_pk_fma_f32 v[176:177], v[176:177], v[170:171], v[168:169]
	v_pk_mul_f32 v[174:175], v[120:121], v[174:175]
	v_pk_mul_f32 v[176:177], v[122:123], v[176:177]
	v_exp_f32_e32 v174, v174
	v_exp_f32_e32 v175, v175
	v_exp_f32_e32 v176, v176
	v_exp_f32_e32 v177, v177
	v_pk_add_f32 v[174:175], v[174:175], v[172:173]
	v_pk_add_f32 v[176:177], v[176:177], v[172:173]
	v_rcp_f32_e32 v174, v174
	v_rcp_f32_e32 v175, v175
	v_rcp_f32_e32 v176, v176
	v_rcp_f32_e32 v177, v177
	v_pk_mul_f32 v[174:175], v[120:121], v[174:175]
	v_pk_mul_f32 v[176:177], v[122:123], v[176:177]
	v_cvt_pk_bf16_f32 v178, v174, v175
	v_cvt_pk_bf16_f32 v179, v176, v177
	global_store_dwordx2 v[160:161], v[178:179], off
	ds_write_b16 v150, v178 offset:64
	ds_write_b16_d16_hi v150, v178 offset:208
	ds_write_b16 v150, v179 offset:352
	ds_write_b16_d16_hi v150, v179 offset:496
	v_pk_mul_f32 v[174:175], v[112:113], v[112:113]
	v_pk_mul_f32 v[176:177], v[114:115], v[114:115]
	v_pk_fma_f32 v[174:175], v[174:175], v[170:171], v[168:169]
	v_pk_fma_f32 v[176:177], v[176:177], v[170:171], v[168:169]
	v_pk_mul_f32 v[174:175], v[112:113], v[174:175]
	v_pk_mul_f32 v[176:177], v[114:115], v[176:177]
	v_exp_f32_e32 v174, v174
	v_exp_f32_e32 v175, v175
	v_exp_f32_e32 v176, v176
	v_exp_f32_e32 v177, v177
	v_pk_add_f32 v[174:175], v[174:175], v[172:173]
	v_pk_add_f32 v[176:177], v[176:177], v[172:173]
	v_rcp_f32_e32 v174, v174
	v_rcp_f32_e32 v175, v175
	v_rcp_f32_e32 v176, v176
	v_rcp_f32_e32 v177, v177
	v_pk_mul_f32 v[174:175], v[112:113], v[174:175]
	v_pk_mul_f32 v[176:177], v[114:115], v[176:177]
	v_cvt_pk_bf16_f32 v182, v174, v175
	v_cvt_pk_bf16_f32 v183, v176, v177
	global_store_dwordx2 v[162:163], v[182:183], off
	ds_write_b16 v150, v182 offset:96
	ds_write_b16_d16_hi v150, v182 offset:240
	ds_write_b16 v150, v183 offset:384
	ds_write_b16_d16_hi v150, v183 offset:528
	v_pk_mul_f32 v[174:175], v[108:109], v[108:109]
	v_pk_mul_f32 v[176:177], v[110:111], v[110:111]
	v_pk_fma_f32 v[174:175], v[174:175], v[170:171], v[168:169]
	v_pk_fma_f32 v[176:177], v[176:177], v[170:171], v[168:169]
	v_pk_mul_f32 v[174:175], v[108:109], v[174:175]
	v_pk_mul_f32 v[176:177], v[110:111], v[176:177]
	v_exp_f32_e32 v174, v174
	v_exp_f32_e32 v175, v175
	v_exp_f32_e32 v176, v176
	v_exp_f32_e32 v177, v177
	v_pk_add_f32 v[174:175], v[174:175], v[172:173]
	v_pk_add_f32 v[176:177], v[176:177], v[172:173]
	v_rcp_f32_e32 v174, v174
	v_rcp_f32_e32 v175, v175
	v_rcp_f32_e32 v176, v176
	v_rcp_f32_e32 v177, v177
	v_pk_mul_f32 v[174:175], v[108:109], v[174:175]
	v_pk_mul_f32 v[176:177], v[110:111], v[176:177]
	v_cvt_pk_bf16_f32 v178, v174, v175
	v_cvt_pk_bf16_f32 v179, v176, v177
	global_store_dwordx2 v[156:157], v[178:179], off offset:32
	ds_write_b16 v150, v178 offset:2304
	ds_write_b16_d16_hi v150, v178 offset:2448
	ds_write_b16 v150, v179 offset:2592
	ds_write_b16_d16_hi v150, v179 offset:2736
	v_pk_mul_f32 v[174:175], v[100:101], v[100:101]
	v_pk_mul_f32 v[176:177], v[102:103], v[102:103]
	v_pk_fma_f32 v[174:175], v[174:175], v[170:171], v[168:169]
	v_pk_fma_f32 v[176:177], v[176:177], v[170:171], v[168:169]
	v_pk_mul_f32 v[174:175], v[100:101], v[174:175]
	v_pk_mul_f32 v[176:177], v[102:103], v[176:177]
	v_exp_f32_e32 v174, v174
	v_exp_f32_e32 v175, v175
	v_exp_f32_e32 v176, v176
	v_exp_f32_e32 v177, v177
	v_pk_add_f32 v[174:175], v[174:175], v[172:173]
	v_pk_add_f32 v[176:177], v[176:177], v[172:173]
	v_rcp_f32_e32 v174, v174
	v_rcp_f32_e32 v175, v175
	v_rcp_f32_e32 v176, v176
	v_rcp_f32_e32 v177, v177
	v_pk_mul_f32 v[174:175], v[100:101], v[174:175]
	v_pk_mul_f32 v[176:177], v[102:103], v[176:177]
	v_cvt_pk_bf16_f32 v182, v174, v175
	v_cvt_pk_bf16_f32 v183, v176, v177
	global_store_dwordx2 v[158:159], v[182:183], off offset:32
	ds_write_b16 v150, v182 offset:2336
	ds_write_b16_d16_hi v150, v182 offset:2480
	ds_write_b16 v150, v183 offset:2624
	ds_write_b16_d16_hi v150, v183 offset:2768
	v_pk_mul_f32 v[174:175], v[104:105], v[104:105]
	v_pk_mul_f32 v[176:177], v[106:107], v[106:107]
	v_pk_fma_f32 v[174:175], v[174:175], v[170:171], v[168:169]
	v_pk_fma_f32 v[176:177], v[176:177], v[170:171], v[168:169]
	v_pk_mul_f32 v[174:175], v[104:105], v[174:175]
	v_pk_mul_f32 v[176:177], v[106:107], v[176:177]
	v_exp_f32_e32 v174, v174
	v_exp_f32_e32 v175, v175
	v_exp_f32_e32 v176, v176
	v_exp_f32_e32 v177, v177
	v_pk_add_f32 v[174:175], v[174:175], v[172:173]
	v_pk_add_f32 v[176:177], v[176:177], v[172:173]
	v_rcp_f32_e32 v174, v174
	v_rcp_f32_e32 v175, v175
	v_rcp_f32_e32 v176, v176
	v_rcp_f32_e32 v177, v177
	v_pk_mul_f32 v[174:175], v[104:105], v[174:175]
	v_pk_mul_f32 v[176:177], v[106:107], v[176:177]
	v_cvt_pk_bf16_f32 v178, v174, v175
	v_cvt_pk_bf16_f32 v179, v176, v177
	global_store_dwordx2 v[160:161], v[178:179], off offset:32
	ds_write_b16 v150, v178 offset:2368
	ds_write_b16_d16_hi v150, v178 offset:2512
	ds_write_b16 v150, v179 offset:2656
	ds_write_b16_d16_hi v150, v179 offset:2800
	v_pk_mul_f32 v[174:175], v[96:97], v[96:97]
	v_pk_mul_f32 v[176:177], v[98:99], v[98:99]
	v_pk_fma_f32 v[174:175], v[174:175], v[170:171], v[168:169]
	v_pk_fma_f32 v[176:177], v[176:177], v[170:171], v[168:169]
	v_pk_mul_f32 v[174:175], v[96:97], v[174:175]
	v_pk_mul_f32 v[176:177], v[98:99], v[176:177]
	v_exp_f32_e32 v174, v174
	v_exp_f32_e32 v175, v175
	v_exp_f32_e32 v176, v176
	v_exp_f32_e32 v177, v177
	v_pk_add_f32 v[174:175], v[174:175], v[172:173]
	v_pk_add_f32 v[176:177], v[176:177], v[172:173]
	v_rcp_f32_e32 v174, v174
	v_rcp_f32_e32 v175, v175
	v_rcp_f32_e32 v176, v176
	v_rcp_f32_e32 v177, v177
	v_pk_mul_f32 v[174:175], v[96:97], v[174:175]
	v_pk_mul_f32 v[176:177], v[98:99], v[176:177]
	v_cvt_pk_bf16_f32 v182, v174, v175
	v_cvt_pk_bf16_f32 v183, v176, v177
	global_store_dwordx2 v[162:163], v[182:183], off offset:32
	ds_write_b16 v150, v182 offset:2400
	ds_write_b16_d16_hi v150, v182 offset:2544
	ds_write_b16 v150, v183 offset:2688
	ds_write_b16_d16_hi v150, v183 offset:2832
	v_pk_mul_f32 v[174:175], v[92:93], v[92:93]
	v_pk_mul_f32 v[176:177], v[94:95], v[94:95]
	v_pk_fma_f32 v[174:175], v[174:175], v[170:171], v[168:169]
	v_pk_fma_f32 v[176:177], v[176:177], v[170:171], v[168:169]
	v_pk_mul_f32 v[174:175], v[92:93], v[174:175]
	v_pk_mul_f32 v[176:177], v[94:95], v[176:177]
	v_exp_f32_e32 v174, v174
	v_exp_f32_e32 v175, v175
	v_exp_f32_e32 v176, v176
	v_exp_f32_e32 v177, v177
	v_pk_add_f32 v[174:175], v[174:175], v[172:173]
	v_pk_add_f32 v[176:177], v[176:177], v[172:173]
	v_rcp_f32_e32 v174, v174
	v_rcp_f32_e32 v175, v175
	v_rcp_f32_e32 v176, v176
	v_rcp_f32_e32 v177, v177
	v_pk_mul_f32 v[174:175], v[92:93], v[174:175]
	v_pk_mul_f32 v[176:177], v[94:95], v[176:177]
	v_cvt_pk_bf16_f32 v178, v174, v175
	v_cvt_pk_bf16_f32 v179, v176, v177
	global_store_dwordx2 v[156:157], v[178:179], off offset:64
	ds_write_b16 v150, v178 offset:4608
	ds_write_b16_d16_hi v150, v178 offset:4752
	ds_write_b16 v150, v179 offset:4896
	ds_write_b16_d16_hi v150, v179 offset:5040
	v_pk_mul_f32 v[174:175], v[84:85], v[84:85]
	v_pk_mul_f32 v[176:177], v[86:87], v[86:87]
	v_pk_fma_f32 v[174:175], v[174:175], v[170:171], v[168:169]
	v_pk_fma_f32 v[176:177], v[176:177], v[170:171], v[168:169]
	v_pk_mul_f32 v[174:175], v[84:85], v[174:175]
	v_pk_mul_f32 v[176:177], v[86:87], v[176:177]
	v_exp_f32_e32 v174, v174
	v_exp_f32_e32 v175, v175
	v_exp_f32_e32 v176, v176
	v_exp_f32_e32 v177, v177
	v_pk_add_f32 v[174:175], v[174:175], v[172:173]
	v_pk_add_f32 v[176:177], v[176:177], v[172:173]
	v_rcp_f32_e32 v174, v174
	v_rcp_f32_e32 v175, v175
	v_rcp_f32_e32 v176, v176
	v_rcp_f32_e32 v177, v177
	v_pk_mul_f32 v[174:175], v[84:85], v[174:175]
	v_pk_mul_f32 v[176:177], v[86:87], v[176:177]
	v_cvt_pk_bf16_f32 v182, v174, v175
	v_cvt_pk_bf16_f32 v183, v176, v177
	global_store_dwordx2 v[158:159], v[182:183], off offset:64
	ds_write_b16 v150, v182 offset:4640
	ds_write_b16_d16_hi v150, v182 offset:4784
	ds_write_b16 v150, v183 offset:4928
	ds_write_b16_d16_hi v150, v183 offset:5072
	v_pk_mul_f32 v[174:175], v[88:89], v[88:89]
	v_pk_mul_f32 v[176:177], v[90:91], v[90:91]
	v_pk_fma_f32 v[174:175], v[174:175], v[170:171], v[168:169]
	v_pk_fma_f32 v[176:177], v[176:177], v[170:171], v[168:169]
	v_pk_mul_f32 v[174:175], v[88:89], v[174:175]
	v_pk_mul_f32 v[176:177], v[90:91], v[176:177]
	v_exp_f32_e32 v174, v174
	v_exp_f32_e32 v175, v175
	v_exp_f32_e32 v176, v176
	v_exp_f32_e32 v177, v177
	v_pk_add_f32 v[174:175], v[174:175], v[172:173]
	v_pk_add_f32 v[176:177], v[176:177], v[172:173]
	v_rcp_f32_e32 v174, v174
	v_rcp_f32_e32 v175, v175
	v_rcp_f32_e32 v176, v176
	v_rcp_f32_e32 v177, v177
	v_pk_mul_f32 v[174:175], v[88:89], v[174:175]
	v_pk_mul_f32 v[176:177], v[90:91], v[176:177]
	v_cvt_pk_bf16_f32 v178, v174, v175
	v_cvt_pk_bf16_f32 v179, v176, v177
	global_store_dwordx2 v[160:161], v[178:179], off offset:64
	ds_write_b16 v150, v178 offset:4672
	ds_write_b16_d16_hi v150, v178 offset:4816
	ds_write_b16 v150, v179 offset:4960
	ds_write_b16_d16_hi v150, v179 offset:5104
	v_pk_mul_f32 v[174:175], v[80:81], v[80:81]
	v_pk_mul_f32 v[176:177], v[82:83], v[82:83]
	v_pk_fma_f32 v[174:175], v[174:175], v[170:171], v[168:169]
	v_pk_fma_f32 v[176:177], v[176:177], v[170:171], v[168:169]
	v_pk_mul_f32 v[174:175], v[80:81], v[174:175]
	v_pk_mul_f32 v[176:177], v[82:83], v[176:177]
	v_exp_f32_e32 v174, v174
	v_exp_f32_e32 v175, v175
	v_exp_f32_e32 v176, v176
	v_exp_f32_e32 v177, v177
	v_pk_add_f32 v[174:175], v[174:175], v[172:173]
	v_pk_add_f32 v[176:177], v[176:177], v[172:173]
	v_rcp_f32_e32 v174, v174
	v_rcp_f32_e32 v175, v175
	v_rcp_f32_e32 v176, v176
	v_rcp_f32_e32 v177, v177
	v_pk_mul_f32 v[174:175], v[80:81], v[174:175]
	v_pk_mul_f32 v[176:177], v[82:83], v[176:177]
	v_cvt_pk_bf16_f32 v182, v174, v175
	v_cvt_pk_bf16_f32 v183, v176, v177
	global_store_dwordx2 v[162:163], v[182:183], off offset:64
	ds_write_b16 v150, v182 offset:4704
	ds_write_b16_d16_hi v150, v182 offset:4848
	ds_write_b16 v150, v183 offset:4992
	ds_write_b16_d16_hi v150, v183 offset:5136
	v_pk_mul_f32 v[174:175], v[76:77], v[76:77]
	v_pk_mul_f32 v[176:177], v[78:79], v[78:79]
	v_pk_fma_f32 v[174:175], v[174:175], v[170:171], v[168:169]
	v_pk_fma_f32 v[176:177], v[176:177], v[170:171], v[168:169]
	v_pk_mul_f32 v[174:175], v[76:77], v[174:175]
	v_pk_mul_f32 v[176:177], v[78:79], v[176:177]
	v_exp_f32_e32 v174, v174
	v_exp_f32_e32 v175, v175
	v_exp_f32_e32 v176, v176
	v_exp_f32_e32 v177, v177
	v_pk_add_f32 v[174:175], v[174:175], v[172:173]
	v_pk_add_f32 v[176:177], v[176:177], v[172:173]
	v_rcp_f32_e32 v174, v174
	v_rcp_f32_e32 v175, v175
	v_rcp_f32_e32 v176, v176
	v_rcp_f32_e32 v177, v177
	v_pk_mul_f32 v[174:175], v[76:77], v[174:175]
	v_pk_mul_f32 v[176:177], v[78:79], v[176:177]
	v_cvt_pk_bf16_f32 v178, v174, v175
	v_cvt_pk_bf16_f32 v179, v176, v177
	global_store_dwordx2 v[156:157], v[178:179], off offset:96
	ds_write_b16 v150, v178 offset:6912
	ds_write_b16_d16_hi v150, v178 offset:7056
	ds_write_b16 v150, v179 offset:7200
	ds_write_b16_d16_hi v150, v179 offset:7344
	v_pk_mul_f32 v[174:175], v[68:69], v[68:69]
	v_pk_mul_f32 v[176:177], v[70:71], v[70:71]
	v_pk_fma_f32 v[174:175], v[174:175], v[170:171], v[168:169]
	v_pk_fma_f32 v[176:177], v[176:177], v[170:171], v[168:169]
	v_pk_mul_f32 v[174:175], v[68:69], v[174:175]
	v_pk_mul_f32 v[176:177], v[70:71], v[176:177]
	v_exp_f32_e32 v174, v174
	v_exp_f32_e32 v175, v175
	v_exp_f32_e32 v176, v176
	v_exp_f32_e32 v177, v177
	v_pk_add_f32 v[174:175], v[174:175], v[172:173]
	v_pk_add_f32 v[176:177], v[176:177], v[172:173]
	v_rcp_f32_e32 v174, v174
	v_rcp_f32_e32 v175, v175
	v_rcp_f32_e32 v176, v176
	v_rcp_f32_e32 v177, v177
	v_pk_mul_f32 v[174:175], v[68:69], v[174:175]
	v_pk_mul_f32 v[176:177], v[70:71], v[176:177]
	v_cvt_pk_bf16_f32 v182, v174, v175
	v_cvt_pk_bf16_f32 v183, v176, v177
	global_store_dwordx2 v[158:159], v[182:183], off offset:96
	ds_write_b16 v150, v182 offset:6944
	ds_write_b16_d16_hi v150, v182 offset:7088
	ds_write_b16 v150, v183 offset:7232
	ds_write_b16_d16_hi v150, v183 offset:7376
	v_pk_mul_f32 v[174:175], v[72:73], v[72:73]
	v_pk_mul_f32 v[176:177], v[74:75], v[74:75]
	v_pk_fma_f32 v[174:175], v[174:175], v[170:171], v[168:169]
	v_pk_fma_f32 v[176:177], v[176:177], v[170:171], v[168:169]
	v_pk_mul_f32 v[174:175], v[72:73], v[174:175]
	v_pk_mul_f32 v[176:177], v[74:75], v[176:177]
	v_exp_f32_e32 v174, v174
	v_exp_f32_e32 v175, v175
	v_exp_f32_e32 v176, v176
	v_exp_f32_e32 v177, v177
	v_pk_add_f32 v[174:175], v[174:175], v[172:173]
	v_pk_add_f32 v[176:177], v[176:177], v[172:173]
	v_rcp_f32_e32 v174, v174
	v_rcp_f32_e32 v175, v175
	v_rcp_f32_e32 v176, v176
	v_rcp_f32_e32 v177, v177
	v_pk_mul_f32 v[174:175], v[72:73], v[174:175]
	v_pk_mul_f32 v[176:177], v[74:75], v[176:177]
	v_cvt_pk_bf16_f32 v178, v174, v175
	v_cvt_pk_bf16_f32 v179, v176, v177
	global_store_dwordx2 v[160:161], v[178:179], off offset:96
	ds_write_b16 v150, v178 offset:6976
	ds_write_b16_d16_hi v150, v178 offset:7120
	ds_write_b16 v150, v179 offset:7264
	ds_write_b16_d16_hi v150, v179 offset:7408
	v_pk_mul_f32 v[174:175], v[64:65], v[64:65]
	v_pk_mul_f32 v[176:177], v[66:67], v[66:67]
	v_pk_fma_f32 v[174:175], v[174:175], v[170:171], v[168:169]
	v_pk_fma_f32 v[176:177], v[176:177], v[170:171], v[168:169]
	v_pk_mul_f32 v[174:175], v[64:65], v[174:175]
	v_pk_mul_f32 v[176:177], v[66:67], v[176:177]
	v_exp_f32_e32 v174, v174
	v_exp_f32_e32 v175, v175
	v_exp_f32_e32 v176, v176
	v_exp_f32_e32 v177, v177
	v_pk_add_f32 v[174:175], v[174:175], v[172:173]
	v_pk_add_f32 v[176:177], v[176:177], v[172:173]
	v_rcp_f32_e32 v174, v174
	v_rcp_f32_e32 v175, v175
	v_rcp_f32_e32 v176, v176
	v_rcp_f32_e32 v177, v177
	v_pk_mul_f32 v[174:175], v[64:65], v[174:175]
	v_pk_mul_f32 v[176:177], v[66:67], v[176:177]
	v_cvt_pk_bf16_f32 v182, v174, v175
	v_cvt_pk_bf16_f32 v183, v176, v177
	global_store_dwordx2 v[162:163], v[182:183], off offset:96
	ds_write_b16 v150, v182 offset:7008
	ds_write_b16_d16_hi v150, v182 offset:7152
	ds_write_b16 v150, v183 offset:7296
	ds_write_b16_d16_hi v150, v183 offset:7440
	v_pk_mul_f32 v[174:175], v[60:61], v[60:61]
	v_pk_mul_f32 v[176:177], v[62:63], v[62:63]
	v_pk_fma_f32 v[174:175], v[174:175], v[170:171], v[168:169]
	v_pk_fma_f32 v[176:177], v[176:177], v[170:171], v[168:169]
	v_pk_mul_f32 v[174:175], v[60:61], v[174:175]
	v_pk_mul_f32 v[176:177], v[62:63], v[176:177]
	v_exp_f32_e32 v174, v174
	v_exp_f32_e32 v175, v175
	v_exp_f32_e32 v176, v176
	v_exp_f32_e32 v177, v177
	v_pk_add_f32 v[174:175], v[174:175], v[172:173]
	v_pk_add_f32 v[176:177], v[176:177], v[172:173]
	v_rcp_f32_e32 v174, v174
	v_rcp_f32_e32 v175, v175
	v_rcp_f32_e32 v176, v176
	v_rcp_f32_e32 v177, v177
	v_pk_mul_f32 v[174:175], v[60:61], v[174:175]
	v_pk_mul_f32 v[176:177], v[62:63], v[176:177]
	v_cvt_pk_bf16_f32 v178, v174, v175
	v_cvt_pk_bf16_f32 v179, v176, v177
	global_store_dwordx2 v[156:157], v[178:179], off offset:128
	ds_write_b16 v150, v178 offset:9216
	ds_write_b16_d16_hi v150, v178 offset:9360
	ds_write_b16 v150, v179 offset:9504
	ds_write_b16_d16_hi v150, v179 offset:9648
	v_pk_mul_f32 v[174:175], v[52:53], v[52:53]
	v_pk_mul_f32 v[176:177], v[54:55], v[54:55]
	v_pk_fma_f32 v[174:175], v[174:175], v[170:171], v[168:169]
	v_pk_fma_f32 v[176:177], v[176:177], v[170:171], v[168:169]
	v_pk_mul_f32 v[174:175], v[52:53], v[174:175]
	v_pk_mul_f32 v[176:177], v[54:55], v[176:177]
	v_exp_f32_e32 v174, v174
	v_exp_f32_e32 v175, v175
	v_exp_f32_e32 v176, v176
	v_exp_f32_e32 v177, v177
	v_pk_add_f32 v[174:175], v[174:175], v[172:173]
	v_pk_add_f32 v[176:177], v[176:177], v[172:173]
	v_rcp_f32_e32 v174, v174
	v_rcp_f32_e32 v175, v175
	v_rcp_f32_e32 v176, v176
	v_rcp_f32_e32 v177, v177
	v_pk_mul_f32 v[174:175], v[52:53], v[174:175]
	v_pk_mul_f32 v[176:177], v[54:55], v[176:177]
	v_cvt_pk_bf16_f32 v182, v174, v175
	v_cvt_pk_bf16_f32 v183, v176, v177
	global_store_dwordx2 v[158:159], v[182:183], off offset:128
	ds_write_b16 v150, v182 offset:9248
	ds_write_b16_d16_hi v150, v182 offset:9392
	ds_write_b16 v150, v183 offset:9536
	ds_write_b16_d16_hi v150, v183 offset:9680
	v_pk_mul_f32 v[174:175], v[56:57], v[56:57]
	v_pk_mul_f32 v[176:177], v[58:59], v[58:59]
	v_pk_fma_f32 v[174:175], v[174:175], v[170:171], v[168:169]
	v_pk_fma_f32 v[176:177], v[176:177], v[170:171], v[168:169]
	v_pk_mul_f32 v[174:175], v[56:57], v[174:175]
	v_pk_mul_f32 v[176:177], v[58:59], v[176:177]
	v_exp_f32_e32 v174, v174
	v_exp_f32_e32 v175, v175
	v_exp_f32_e32 v176, v176
	v_exp_f32_e32 v177, v177
	v_pk_add_f32 v[174:175], v[174:175], v[172:173]
	v_pk_add_f32 v[176:177], v[176:177], v[172:173]
	v_rcp_f32_e32 v174, v174
	v_rcp_f32_e32 v175, v175
	v_rcp_f32_e32 v176, v176
	v_rcp_f32_e32 v177, v177
	v_pk_mul_f32 v[174:175], v[56:57], v[174:175]
	v_pk_mul_f32 v[176:177], v[58:59], v[176:177]
	v_cvt_pk_bf16_f32 v178, v174, v175
	v_cvt_pk_bf16_f32 v179, v176, v177
	global_store_dwordx2 v[160:161], v[178:179], off offset:128
	ds_write_b16 v150, v178 offset:9280
	ds_write_b16_d16_hi v150, v178 offset:9424
	ds_write_b16 v150, v179 offset:9568
	ds_write_b16_d16_hi v150, v179 offset:9712
	v_pk_mul_f32 v[174:175], v[48:49], v[48:49]
	v_pk_mul_f32 v[176:177], v[50:51], v[50:51]
	v_pk_fma_f32 v[174:175], v[174:175], v[170:171], v[168:169]
	v_pk_fma_f32 v[176:177], v[176:177], v[170:171], v[168:169]
	v_pk_mul_f32 v[174:175], v[48:49], v[174:175]
	v_pk_mul_f32 v[176:177], v[50:51], v[176:177]
	v_exp_f32_e32 v174, v174
	v_exp_f32_e32 v175, v175
	v_exp_f32_e32 v176, v176
	v_exp_f32_e32 v177, v177
	v_pk_add_f32 v[174:175], v[174:175], v[172:173]
	v_pk_add_f32 v[176:177], v[176:177], v[172:173]
	v_rcp_f32_e32 v174, v174
	v_rcp_f32_e32 v175, v175
	v_rcp_f32_e32 v176, v176
	v_rcp_f32_e32 v177, v177
	v_pk_mul_f32 v[174:175], v[48:49], v[174:175]
	v_pk_mul_f32 v[176:177], v[50:51], v[176:177]
	v_cvt_pk_bf16_f32 v182, v174, v175
	v_cvt_pk_bf16_f32 v183, v176, v177
	global_store_dwordx2 v[162:163], v[182:183], off offset:128
	ds_write_b16 v150, v182 offset:9312
	ds_write_b16_d16_hi v150, v182 offset:9456
	ds_write_b16 v150, v183 offset:9600
	ds_write_b16_d16_hi v150, v183 offset:9744
	v_pk_mul_f32 v[174:175], v[44:45], v[44:45]
	v_pk_mul_f32 v[176:177], v[46:47], v[46:47]
	v_pk_fma_f32 v[174:175], v[174:175], v[170:171], v[168:169]
	v_pk_fma_f32 v[176:177], v[176:177], v[170:171], v[168:169]
	v_pk_mul_f32 v[174:175], v[44:45], v[174:175]
	v_pk_mul_f32 v[176:177], v[46:47], v[176:177]
	v_exp_f32_e32 v174, v174
	v_exp_f32_e32 v175, v175
	v_exp_f32_e32 v176, v176
	v_exp_f32_e32 v177, v177
	v_pk_add_f32 v[174:175], v[174:175], v[172:173]
	v_pk_add_f32 v[176:177], v[176:177], v[172:173]
	v_rcp_f32_e32 v174, v174
	v_rcp_f32_e32 v175, v175
	v_rcp_f32_e32 v176, v176
	v_rcp_f32_e32 v177, v177
	v_pk_mul_f32 v[174:175], v[44:45], v[174:175]
	v_pk_mul_f32 v[176:177], v[46:47], v[176:177]
	v_cvt_pk_bf16_f32 v178, v174, v175
	v_cvt_pk_bf16_f32 v179, v176, v177
	global_store_dwordx2 v[156:157], v[178:179], off offset:160
	ds_write_b16 v150, v178 offset:11520
	ds_write_b16_d16_hi v150, v178 offset:11664
	ds_write_b16 v150, v179 offset:11808
	ds_write_b16_d16_hi v150, v179 offset:11952
	v_pk_mul_f32 v[174:175], v[36:37], v[36:37]
	v_pk_mul_f32 v[176:177], v[38:39], v[38:39]
	v_pk_fma_f32 v[174:175], v[174:175], v[170:171], v[168:169]
	v_pk_fma_f32 v[176:177], v[176:177], v[170:171], v[168:169]
	v_pk_mul_f32 v[174:175], v[36:37], v[174:175]
	v_pk_mul_f32 v[176:177], v[38:39], v[176:177]
	v_exp_f32_e32 v174, v174
	v_exp_f32_e32 v175, v175
	v_exp_f32_e32 v176, v176
	v_exp_f32_e32 v177, v177
	v_pk_add_f32 v[174:175], v[174:175], v[172:173]
	v_pk_add_f32 v[176:177], v[176:177], v[172:173]
	v_rcp_f32_e32 v174, v174
	v_rcp_f32_e32 v175, v175
	v_rcp_f32_e32 v176, v176
	v_rcp_f32_e32 v177, v177
	v_pk_mul_f32 v[174:175], v[36:37], v[174:175]
	v_pk_mul_f32 v[176:177], v[38:39], v[176:177]
	v_cvt_pk_bf16_f32 v182, v174, v175
	v_cvt_pk_bf16_f32 v183, v176, v177
	global_store_dwordx2 v[158:159], v[182:183], off offset:160
	ds_write_b16 v150, v182 offset:11552
	ds_write_b16_d16_hi v150, v182 offset:11696
	ds_write_b16 v150, v183 offset:11840
	ds_write_b16_d16_hi v150, v183 offset:11984
	v_pk_mul_f32 v[174:175], v[40:41], v[40:41]
	v_pk_mul_f32 v[176:177], v[42:43], v[42:43]
	v_pk_fma_f32 v[174:175], v[174:175], v[170:171], v[168:169]
	v_pk_fma_f32 v[176:177], v[176:177], v[170:171], v[168:169]
	v_pk_mul_f32 v[174:175], v[40:41], v[174:175]
	v_pk_mul_f32 v[176:177], v[42:43], v[176:177]
	v_exp_f32_e32 v174, v174
	v_exp_f32_e32 v175, v175
	v_exp_f32_e32 v176, v176
	v_exp_f32_e32 v177, v177
	v_pk_add_f32 v[174:175], v[174:175], v[172:173]
	v_pk_add_f32 v[176:177], v[176:177], v[172:173]
	v_rcp_f32_e32 v174, v174
	v_rcp_f32_e32 v175, v175
	v_rcp_f32_e32 v176, v176
	v_rcp_f32_e32 v177, v177
	v_pk_mul_f32 v[174:175], v[40:41], v[174:175]
	v_pk_mul_f32 v[176:177], v[42:43], v[176:177]
	v_cvt_pk_bf16_f32 v178, v174, v175
	v_cvt_pk_bf16_f32 v179, v176, v177
	global_store_dwordx2 v[160:161], v[178:179], off offset:160
	ds_write_b16 v150, v178 offset:11584
	ds_write_b16_d16_hi v150, v178 offset:11728
	ds_write_b16 v150, v179 offset:11872
	ds_write_b16_d16_hi v150, v179 offset:12016
	v_pk_mul_f32 v[174:175], v[32:33], v[32:33]
	v_pk_mul_f32 v[176:177], v[34:35], v[34:35]
	v_pk_fma_f32 v[174:175], v[174:175], v[170:171], v[168:169]
	v_pk_fma_f32 v[176:177], v[176:177], v[170:171], v[168:169]
	v_pk_mul_f32 v[174:175], v[32:33], v[174:175]
	v_pk_mul_f32 v[176:177], v[34:35], v[176:177]
	v_exp_f32_e32 v174, v174
	v_exp_f32_e32 v175, v175
	v_exp_f32_e32 v176, v176
	v_exp_f32_e32 v177, v177
	v_pk_add_f32 v[174:175], v[174:175], v[172:173]
	v_pk_add_f32 v[176:177], v[176:177], v[172:173]
	v_rcp_f32_e32 v174, v174
	v_rcp_f32_e32 v175, v175
	v_rcp_f32_e32 v176, v176
	v_rcp_f32_e32 v177, v177
	v_pk_mul_f32 v[174:175], v[32:33], v[174:175]
	v_pk_mul_f32 v[176:177], v[34:35], v[176:177]
	v_cvt_pk_bf16_f32 v182, v174, v175
	v_cvt_pk_bf16_f32 v183, v176, v177
	global_store_dwordx2 v[162:163], v[182:183], off offset:160
	ds_write_b16 v150, v182 offset:11616
	ds_write_b16_d16_hi v150, v182 offset:11760
	ds_write_b16 v150, v183 offset:11904
	ds_write_b16_d16_hi v150, v183 offset:12048
	v_pk_mul_f32 v[174:175], v[28:29], v[28:29]
	v_pk_mul_f32 v[176:177], v[30:31], v[30:31]
	v_pk_fma_f32 v[174:175], v[174:175], v[170:171], v[168:169]
	v_pk_fma_f32 v[176:177], v[176:177], v[170:171], v[168:169]
	v_pk_mul_f32 v[174:175], v[28:29], v[174:175]
	v_pk_mul_f32 v[176:177], v[30:31], v[176:177]
	v_exp_f32_e32 v174, v174
	v_exp_f32_e32 v175, v175
	v_exp_f32_e32 v176, v176
	v_exp_f32_e32 v177, v177
	v_pk_add_f32 v[174:175], v[174:175], v[172:173]
	v_pk_add_f32 v[176:177], v[176:177], v[172:173]
	v_rcp_f32_e32 v174, v174
	v_rcp_f32_e32 v175, v175
	v_rcp_f32_e32 v176, v176
	v_rcp_f32_e32 v177, v177
	v_pk_mul_f32 v[174:175], v[28:29], v[174:175]
	v_pk_mul_f32 v[176:177], v[30:31], v[176:177]
	v_cvt_pk_bf16_f32 v178, v174, v175
	v_cvt_pk_bf16_f32 v179, v176, v177
	global_store_dwordx2 v[156:157], v[178:179], off offset:192
	ds_write_b16 v150, v178 offset:13824
	ds_write_b16_d16_hi v150, v178 offset:13968
	ds_write_b16 v150, v179 offset:14112
	ds_write_b16_d16_hi v150, v179 offset:14256
	v_pk_mul_f32 v[174:175], v[16:17], v[16:17]
	v_pk_mul_f32 v[176:177], v[18:19], v[18:19]
	v_pk_fma_f32 v[174:175], v[174:175], v[170:171], v[168:169]
	v_pk_fma_f32 v[176:177], v[176:177], v[170:171], v[168:169]
	v_pk_mul_f32 v[174:175], v[16:17], v[174:175]
	v_pk_mul_f32 v[176:177], v[18:19], v[176:177]
	v_exp_f32_e32 v174, v174
	v_exp_f32_e32 v175, v175
	v_exp_f32_e32 v176, v176
	v_exp_f32_e32 v177, v177
	v_pk_add_f32 v[174:175], v[174:175], v[172:173]
	v_pk_add_f32 v[176:177], v[176:177], v[172:173]
	v_rcp_f32_e32 v174, v174
	v_rcp_f32_e32 v175, v175
	v_rcp_f32_e32 v176, v176
	v_rcp_f32_e32 v177, v177
	v_pk_mul_f32 v[174:175], v[16:17], v[174:175]
	v_pk_mul_f32 v[176:177], v[18:19], v[176:177]
	v_cvt_pk_bf16_f32 v182, v174, v175
	v_cvt_pk_bf16_f32 v183, v176, v177
	global_store_dwordx2 v[158:159], v[182:183], off offset:192
	ds_write_b16 v150, v182 offset:13856
	ds_write_b16_d16_hi v150, v182 offset:14000
	ds_write_b16 v150, v183 offset:14144
	ds_write_b16_d16_hi v150, v183 offset:14288
	v_pk_mul_f32 v[174:175], v[24:25], v[24:25]
	v_pk_mul_f32 v[176:177], v[26:27], v[26:27]
	v_pk_fma_f32 v[174:175], v[174:175], v[170:171], v[168:169]
	v_pk_fma_f32 v[176:177], v[176:177], v[170:171], v[168:169]
	v_pk_mul_f32 v[174:175], v[24:25], v[174:175]
	v_pk_mul_f32 v[176:177], v[26:27], v[176:177]
	v_exp_f32_e32 v174, v174
	v_exp_f32_e32 v175, v175
	v_exp_f32_e32 v176, v176
	v_exp_f32_e32 v177, v177
	v_pk_add_f32 v[174:175], v[174:175], v[172:173]
	v_pk_add_f32 v[176:177], v[176:177], v[172:173]
	v_rcp_f32_e32 v174, v174
	v_rcp_f32_e32 v175, v175
	v_rcp_f32_e32 v176, v176
	v_rcp_f32_e32 v177, v177
	v_pk_mul_f32 v[174:175], v[24:25], v[174:175]
	v_pk_mul_f32 v[176:177], v[26:27], v[176:177]
	v_cvt_pk_bf16_f32 v178, v174, v175
	v_cvt_pk_bf16_f32 v179, v176, v177
	global_store_dwordx2 v[160:161], v[178:179], off offset:192
	ds_write_b16 v150, v178 offset:13888
	ds_write_b16_d16_hi v150, v178 offset:14032
	ds_write_b16 v150, v179 offset:14176
	ds_write_b16_d16_hi v150, v179 offset:14320
	v_pk_mul_f32 v[174:175], v[12:13], v[12:13]
	v_pk_mul_f32 v[176:177], v[14:15], v[14:15]
	v_pk_fma_f32 v[174:175], v[174:175], v[170:171], v[168:169]
	v_pk_fma_f32 v[176:177], v[176:177], v[170:171], v[168:169]
	v_pk_mul_f32 v[174:175], v[12:13], v[174:175]
	v_pk_mul_f32 v[176:177], v[14:15], v[176:177]
	v_exp_f32_e32 v174, v174
	v_exp_f32_e32 v175, v175
	v_exp_f32_e32 v176, v176
	v_exp_f32_e32 v177, v177
	v_pk_add_f32 v[174:175], v[174:175], v[172:173]
	v_pk_add_f32 v[176:177], v[176:177], v[172:173]
	v_rcp_f32_e32 v174, v174
	v_rcp_f32_e32 v175, v175
	v_rcp_f32_e32 v176, v176
	v_rcp_f32_e32 v177, v177
	v_pk_mul_f32 v[174:175], v[12:13], v[174:175]
	v_pk_mul_f32 v[176:177], v[14:15], v[176:177]
	v_cvt_pk_bf16_f32 v182, v174, v175
	v_cvt_pk_bf16_f32 v183, v176, v177
	global_store_dwordx2 v[162:163], v[182:183], off offset:192
	ds_write_b16 v150, v182 offset:13920
	ds_write_b16_d16_hi v150, v182 offset:14064
	ds_write_b16 v150, v183 offset:14208
	ds_write_b16_d16_hi v150, v183 offset:14352
	v_pk_mul_f32 v[174:175], v[4:5], v[4:5]
	v_pk_mul_f32 v[176:177], v[6:7], v[6:7]
	v_pk_fma_f32 v[174:175], v[174:175], v[170:171], v[168:169]
	v_pk_fma_f32 v[176:177], v[176:177], v[170:171], v[168:169]
	v_pk_mul_f32 v[174:175], v[4:5], v[174:175]
	v_pk_mul_f32 v[176:177], v[6:7], v[176:177]
	v_exp_f32_e32 v174, v174
	v_exp_f32_e32 v175, v175
	v_exp_f32_e32 v176, v176
	v_exp_f32_e32 v177, v177
	v_pk_add_f32 v[174:175], v[174:175], v[172:173]
	v_pk_add_f32 v[176:177], v[176:177], v[172:173]
	v_rcp_f32_e32 v174, v174
	v_rcp_f32_e32 v175, v175
	v_rcp_f32_e32 v176, v176
	v_rcp_f32_e32 v177, v177
	v_pk_mul_f32 v[174:175], v[4:5], v[174:175]
	v_pk_mul_f32 v[176:177], v[6:7], v[176:177]
	v_cvt_pk_bf16_f32 v178, v174, v175
	v_cvt_pk_bf16_f32 v179, v176, v177
	global_store_dwordx2 v[156:157], v[178:179], off offset:224
	ds_write_b16 v150, v178 offset:16128
	ds_write_b16_d16_hi v150, v178 offset:16272
	ds_write_b16 v150, v179 offset:16416
	ds_write_b16_d16_hi v150, v179 offset:16560
	v_pk_mul_f32 v[174:175], v[0:1], v[0:1]
	v_pk_mul_f32 v[176:177], v[2:3], v[2:3]
	v_pk_fma_f32 v[174:175], v[174:175], v[170:171], v[168:169]
	v_pk_fma_f32 v[176:177], v[176:177], v[170:171], v[168:169]
	v_pk_mul_f32 v[174:175], v[0:1], v[174:175]
	v_pk_mul_f32 v[176:177], v[2:3], v[176:177]
	v_exp_f32_e32 v174, v174
	v_exp_f32_e32 v175, v175
	v_exp_f32_e32 v176, v176
	v_exp_f32_e32 v177, v177
	v_pk_add_f32 v[174:175], v[174:175], v[172:173]
	v_pk_add_f32 v[176:177], v[176:177], v[172:173]
	v_rcp_f32_e32 v174, v174
	v_rcp_f32_e32 v175, v175
	v_rcp_f32_e32 v176, v176
	v_rcp_f32_e32 v177, v177
	v_pk_mul_f32 v[174:175], v[0:1], v[174:175]
	v_pk_mul_f32 v[176:177], v[2:3], v[176:177]
	v_cvt_pk_bf16_f32 v182, v174, v175
	v_cvt_pk_bf16_f32 v183, v176, v177
	global_store_dwordx2 v[158:159], v[182:183], off offset:224
	ds_write_b16 v150, v182 offset:16160
	ds_write_b16_d16_hi v150, v182 offset:16304
	ds_write_b16 v150, v183 offset:16448
	ds_write_b16_d16_hi v150, v183 offset:16592
	v_pk_mul_f32 v[174:175], v[20:21], v[20:21]
	v_pk_mul_f32 v[176:177], v[22:23], v[22:23]
	v_pk_fma_f32 v[174:175], v[174:175], v[170:171], v[168:169]
	v_pk_fma_f32 v[176:177], v[176:177], v[170:171], v[168:169]
	v_pk_mul_f32 v[174:175], v[20:21], v[174:175]
	v_pk_mul_f32 v[176:177], v[22:23], v[176:177]
	v_exp_f32_e32 v174, v174
	v_exp_f32_e32 v175, v175
	v_exp_f32_e32 v176, v176
	v_exp_f32_e32 v177, v177
	v_pk_add_f32 v[174:175], v[174:175], v[172:173]
	v_pk_add_f32 v[176:177], v[176:177], v[172:173]
	v_rcp_f32_e32 v174, v174
	v_rcp_f32_e32 v175, v175
	v_rcp_f32_e32 v176, v176
	v_rcp_f32_e32 v177, v177
	v_pk_mul_f32 v[174:175], v[20:21], v[174:175]
	v_pk_mul_f32 v[176:177], v[22:23], v[176:177]
	v_cvt_pk_bf16_f32 v178, v174, v175
	v_cvt_pk_bf16_f32 v179, v176, v177
	global_store_dwordx2 v[160:161], v[178:179], off offset:224
	ds_write_b16 v150, v178 offset:16192
	ds_write_b16_d16_hi v150, v178 offset:16336
	ds_write_b16 v150, v179 offset:16480
	ds_write_b16_d16_hi v150, v179 offset:16624
	v_pk_mul_f32 v[174:175], v[8:9], v[8:9]
	v_pk_mul_f32 v[176:177], v[10:11], v[10:11]
	v_pk_fma_f32 v[174:175], v[174:175], v[170:171], v[168:169]
	v_pk_fma_f32 v[176:177], v[176:177], v[170:171], v[168:169]
	v_pk_mul_f32 v[174:175], v[8:9], v[174:175]
	v_pk_mul_f32 v[176:177], v[10:11], v[176:177]
	v_exp_f32_e32 v174, v174
	v_exp_f32_e32 v175, v175
	v_exp_f32_e32 v176, v176
	v_exp_f32_e32 v177, v177
	v_pk_add_f32 v[174:175], v[174:175], v[172:173]
	v_pk_add_f32 v[176:177], v[176:177], v[172:173]
	v_rcp_f32_e32 v174, v174
	v_rcp_f32_e32 v175, v175
	v_rcp_f32_e32 v176, v176
	v_rcp_f32_e32 v177, v177
	v_pk_mul_f32 v[174:175], v[8:9], v[174:175]
	v_pk_mul_f32 v[176:177], v[10:11], v[176:177]
	v_cvt_pk_bf16_f32 v182, v174, v175
	v_cvt_pk_bf16_f32 v183, v176, v177
	global_store_dwordx2 v[162:163], v[182:183], off offset:224
	ds_write_b16 v150, v182 offset:16224
	ds_write_b16_d16_hi v150, v182 offset:16368
	ds_write_b16 v150, v183 offset:16512
	ds_write_b16_d16_hi v150, v183 offset:16656
	s_waitcnt lgkmcnt(0)
	ds_read_b128 v[184:187], v152
	ds_read_b128 v[188:191], v152 offset:1152
	ds_read_b128 v[192:195], v152 offset:2304
	ds_read_b128 v[196:199], v152 offset:3456
	ds_read_b128 v[200:203], v152 offset:4608
	ds_read_b128 v[204:207], v152 offset:5760
	ds_read_b128 v[208:211], v152 offset:6912
	ds_read_b128 v[212:215], v152 offset:8064
	s_waitcnt lgkmcnt(7)
	v_lshlrev_b32_e32 v134, 16, v184
	v_and_b32_e32 v135, 0xffff0000, v184
	v_lshlrev_b32_e32 v136, 16, v185
	v_and_b32_e32 v137, 0xffff0000, v185
	v_lshlrev_b32_e32 v138, 16, v186
	v_and_b32_e32 v139, 0xffff0000, v186
	v_lshlrev_b32_e32 v140, 16, v187
	v_and_b32_e32 v141, 0xffff0000, v187
	v_pk_mul_f32 v[142:143], v[134:135], v[134:135]
	v_pk_mul_f32 v[144:145], v[136:137], v[136:137]
	v_pk_mul_f32 v[248:249], v[138:139], v[138:139]
	v_pk_mul_f32 v[250:251], v[140:141], v[140:141]
	v_add_f32_e32 v184, v134, v135
	v_add_f32_e32 v185, v142, v143
	v_add_f32_e32 v158, v136, v137
	v_add_f32_e32 v159, v144, v145
	v_add_f32_e32 v160, v138, v139
	v_add_f32_e32 v161, v248, v249
	v_add_f32_e32 v162, v140, v141
	v_add_f32_e32 v163, v250, v251
	v_pk_add_f32 v[184:185], v[184:185], v[158:159]
	v_pk_add_f32 v[184:185], v[184:185], v[160:161]
	v_pk_add_f32 v[184:185], v[184:185], v[162:163]
	ds_read_b128 v[216:219], v152 offset:9216
	s_waitcnt lgkmcnt(7)
	v_lshlrev_b32_e32 v134, 16, v188
	v_and_b32_e32 v135, 0xffff0000, v188
	v_lshlrev_b32_e32 v136, 16, v189
	v_and_b32_e32 v137, 0xffff0000, v189
	v_lshlrev_b32_e32 v138, 16, v190
	v_and_b32_e32 v139, 0xffff0000, v190
	v_lshlrev_b32_e32 v140, 16, v191
	v_and_b32_e32 v141, 0xffff0000, v191
	v_pk_mul_f32 v[142:143], v[134:135], v[134:135]
	v_pk_mul_f32 v[144:145], v[136:137], v[136:137]
	v_pk_mul_f32 v[248:249], v[138:139], v[138:139]
	v_pk_mul_f32 v[250:251], v[140:141], v[140:141]
	v_add_f32_e32 v188, v134, v135
	v_add_f32_e32 v189, v142, v143
	v_add_f32_e32 v158, v136, v137
	v_add_f32_e32 v159, v144, v145
	v_add_f32_e32 v160, v138, v139
	v_add_f32_e32 v161, v248, v249
	v_add_f32_e32 v162, v140, v141
	v_add_f32_e32 v163, v250, v251
	v_pk_add_f32 v[188:189], v[188:189], v[158:159]
	v_pk_add_f32 v[188:189], v[188:189], v[160:161]
	v_pk_add_f32 v[188:189], v[188:189], v[162:163]
	ds_read_b128 v[220:223], v152 offset:10368
	s_nop 1
	v_add_f32_dpp v184, v184, v184 quad_perm:[1,0,3,2] row_mask:0xf bank_mask:0xf
	v_add_f32_dpp v185, v185, v185 quad_perm:[1,0,3,2] row_mask:0xf bank_mask:0xf
	v_add_f32_dpp v188, v188, v188 quad_perm:[1,0,3,2] row_mask:0xf bank_mask:0xf
	v_add_f32_dpp v189, v189, v189 quad_perm:[1,0,3,2] row_mask:0xf bank_mask:0xf
	v_add_f32_dpp v184, v184, v184 quad_perm:[2,3,0,1] row_mask:0xf bank_mask:0xf
	v_add_f32_dpp v185, v185, v185 quad_perm:[2,3,0,1] row_mask:0xf bank_mask:0xf
	v_add_f32_dpp v188, v188, v188 quad_perm:[2,3,0,1] row_mask:0xf bank_mask:0xf
	v_add_f32_dpp v189, v189, v189 quad_perm:[2,3,0,1] row_mask:0xf bank_mask:0xf
	v_add_f32_dpp v184, v184, v184 row_half_mirror row_mask:0xf bank_mask:0xf
	v_add_f32_dpp v185, v185, v185 row_half_mirror row_mask:0xf bank_mask:0xf
	v_add_f32_dpp v188, v188, v188 row_half_mirror row_mask:0xf bank_mask:0xf
	v_add_f32_dpp v189, v189, v189 row_half_mirror row_mask:0xf bank_mask:0xf
	s_waitcnt lgkmcnt(7)
	v_lshlrev_b32_e32 v134, 16, v192
	v_and_b32_e32 v135, 0xffff0000, v192
	v_lshlrev_b32_e32 v136, 16, v193
	v_and_b32_e32 v137, 0xffff0000, v193
	v_lshlrev_b32_e32 v138, 16, v194
	v_and_b32_e32 v139, 0xffff0000, v194
	v_lshlrev_b32_e32 v140, 16, v195
	v_and_b32_e32 v141, 0xffff0000, v195
	v_pk_mul_f32 v[142:143], v[134:135], v[134:135]
	v_pk_mul_f32 v[144:145], v[136:137], v[136:137]
	v_pk_mul_f32 v[248:249], v[138:139], v[138:139]
	v_pk_mul_f32 v[250:251], v[140:141], v[140:141]
	v_add_f32_e32 v192, v134, v135
	v_add_f32_e32 v193, v142, v143
	v_add_f32_e32 v158, v136, v137
	v_add_f32_e32 v159, v144, v145
	v_add_f32_e32 v160, v138, v139
	v_add_f32_e32 v161, v248, v249
	v_add_f32_e32 v162, v140, v141
	v_add_f32_e32 v163, v250, v251
	v_pk_add_f32 v[192:193], v[192:193], v[158:159]
	v_pk_add_f32 v[192:193], v[192:193], v[160:161]
	v_pk_add_f32 v[192:193], v[192:193], v[162:163]
	ds_read_b128 v[224:227], v152 offset:11520
	s_waitcnt lgkmcnt(7)
	v_lshlrev_b32_e32 v134, 16, v196
	v_and_b32_e32 v135, 0xffff0000, v196
	v_lshlrev_b32_e32 v136, 16, v197
	v_and_b32_e32 v137, 0xffff0000, v197
	v_lshlrev_b32_e32 v138, 16, v198
	v_and_b32_e32 v139, 0xffff0000, v198
	v_lshlrev_b32_e32 v140, 16, v199
	v_and_b32_e32 v141, 0xffff0000, v199
	v_pk_mul_f32 v[142:143], v[134:135], v[134:135]
	v_pk_mul_f32 v[144:145], v[136:137], v[136:137]
	v_pk_mul_f32 v[248:249], v[138:139], v[138:139]
	v_pk_mul_f32 v[250:251], v[140:141], v[140:141]
	v_add_f32_e32 v196, v134, v135
	v_add_f32_e32 v197, v142, v143
	v_add_f32_e32 v158, v136, v137
	v_add_f32_e32 v159, v144, v145
	v_add_f32_e32 v160, v138, v139
	v_add_f32_e32 v161, v248, v249
	v_add_f32_e32 v162, v140, v141
	v_add_f32_e32 v163, v250, v251
	v_pk_add_f32 v[196:197], v[196:197], v[158:159]
	v_pk_add_f32 v[196:197], v[196:197], v[160:161]
	v_pk_add_f32 v[196:197], v[196:197], v[162:163]
	ds_read_b128 v[228:231], v152 offset:12672
	s_nop 1
	v_add_f32_dpp v192, v192, v192 quad_perm:[1,0,3,2] row_mask:0xf bank_mask:0xf
	v_add_f32_dpp v193, v193, v193 quad_perm:[1,0,3,2] row_mask:0xf bank_mask:0xf
	v_add_f32_dpp v196, v196, v196 quad_perm:[1,0,3,2] row_mask:0xf bank_mask:0xf
	v_add_f32_dpp v197, v197, v197 quad_perm:[1,0,3,2] row_mask:0xf bank_mask:0xf
	v_add_f32_dpp v192, v192, v192 quad_perm:[2,3,0,1] row_mask:0xf bank_mask:0xf
	v_add_f32_dpp v193, v193, v193 quad_perm:[2,3,0,1] row_mask:0xf bank_mask:0xf
	v_add_f32_dpp v196, v196, v196 quad_perm:[2,3,0,1] row_mask:0xf bank_mask:0xf
	v_add_f32_dpp v197, v197, v197 quad_perm:[2,3,0,1] row_mask:0xf bank_mask:0xf
	v_add_f32_dpp v192, v192, v192 row_half_mirror row_mask:0xf bank_mask:0xf
	v_add_f32_dpp v193, v193, v193 row_half_mirror row_mask:0xf bank_mask:0xf
	v_add_f32_dpp v196, v196, v196 row_half_mirror row_mask:0xf bank_mask:0xf
	v_add_f32_dpp v197, v197, v197 row_half_mirror row_mask:0xf bank_mask:0xf
	s_waitcnt lgkmcnt(7)
	v_lshlrev_b32_e32 v134, 16, v200
	v_and_b32_e32 v135, 0xffff0000, v200
	v_lshlrev_b32_e32 v136, 16, v201
	v_and_b32_e32 v137, 0xffff0000, v201
	v_lshlrev_b32_e32 v138, 16, v202
	v_and_b32_e32 v139, 0xffff0000, v202
	v_lshlrev_b32_e32 v140, 16, v203
	v_and_b32_e32 v141, 0xffff0000, v203
	v_pk_mul_f32 v[142:143], v[134:135], v[134:135]
	v_pk_mul_f32 v[144:145], v[136:137], v[136:137]
	v_pk_mul_f32 v[248:249], v[138:139], v[138:139]
	v_pk_mul_f32 v[250:251], v[140:141], v[140:141]
	v_add_f32_e32 v200, v134, v135
	v_add_f32_e32 v201, v142, v143
	v_add_f32_e32 v158, v136, v137
	v_add_f32_e32 v159, v144, v145
	v_add_f32_e32 v160, v138, v139
	v_add_f32_e32 v161, v248, v249
	v_add_f32_e32 v162, v140, v141
	v_add_f32_e32 v163, v250, v251
	v_pk_add_f32 v[200:201], v[200:201], v[158:159]
	v_pk_add_f32 v[200:201], v[200:201], v[160:161]
	v_pk_add_f32 v[200:201], v[200:201], v[162:163]
	ds_read_b128 v[232:235], v152 offset:13824
	s_waitcnt lgkmcnt(7)
	v_lshlrev_b32_e32 v134, 16, v204
	v_and_b32_e32 v135, 0xffff0000, v204
	v_lshlrev_b32_e32 v136, 16, v205
	v_and_b32_e32 v137, 0xffff0000, v205
	v_lshlrev_b32_e32 v138, 16, v206
	v_and_b32_e32 v139, 0xffff0000, v206
	v_lshlrev_b32_e32 v140, 16, v207
	v_and_b32_e32 v141, 0xffff0000, v207
	v_pk_mul_f32 v[142:143], v[134:135], v[134:135]
	v_pk_mul_f32 v[144:145], v[136:137], v[136:137]
	v_pk_mul_f32 v[248:249], v[138:139], v[138:139]
	v_pk_mul_f32 v[250:251], v[140:141], v[140:141]
	v_add_f32_e32 v204, v134, v135
	v_add_f32_e32 v205, v142, v143
	v_add_f32_e32 v158, v136, v137
	v_add_f32_e32 v159, v144, v145
	v_add_f32_e32 v160, v138, v139
	v_add_f32_e32 v161, v248, v249
	v_add_f32_e32 v162, v140, v141
	v_add_f32_e32 v163, v250, v251
	v_pk_add_f32 v[204:205], v[204:205], v[158:159]
	v_pk_add_f32 v[204:205], v[204:205], v[160:161]
	v_pk_add_f32 v[204:205], v[204:205], v[162:163]
	ds_read_b128 v[236:239], v152 offset:14976
	s_nop 1
	v_add_f32_dpp v200, v200, v200 quad_perm:[1,0,3,2] row_mask:0xf bank_mask:0xf
	v_add_f32_dpp v201, v201, v201 quad_perm:[1,0,3,2] row_mask:0xf bank_mask:0xf
	v_add_f32_dpp v204, v204, v204 quad_perm:[1,0,3,2] row_mask:0xf bank_mask:0xf
	v_add_f32_dpp v205, v205, v205 quad_perm:[1,0,3,2] row_mask:0xf bank_mask:0xf
	v_add_f32_dpp v200, v200, v200 quad_perm:[2,3,0,1] row_mask:0xf bank_mask:0xf
	v_add_f32_dpp v201, v201, v201 quad_perm:[2,3,0,1] row_mask:0xf bank_mask:0xf
	v_add_f32_dpp v204, v204, v204 quad_perm:[2,3,0,1] row_mask:0xf bank_mask:0xf
	v_add_f32_dpp v205, v205, v205 quad_perm:[2,3,0,1] row_mask:0xf bank_mask:0xf
	v_add_f32_dpp v200, v200, v200 row_half_mirror row_mask:0xf bank_mask:0xf
	v_add_f32_dpp v201, v201, v201 row_half_mirror row_mask:0xf bank_mask:0xf
	v_add_f32_dpp v204, v204, v204 row_half_mirror row_mask:0xf bank_mask:0xf
	v_add_f32_dpp v205, v205, v205 row_half_mirror row_mask:0xf bank_mask:0xf
	s_waitcnt lgkmcnt(7)
	v_lshlrev_b32_e32 v134, 16, v208
	v_and_b32_e32 v135, 0xffff0000, v208
	v_lshlrev_b32_e32 v136, 16, v209
	v_and_b32_e32 v137, 0xffff0000, v209
	v_lshlrev_b32_e32 v138, 16, v210
	v_and_b32_e32 v139, 0xffff0000, v210
	v_lshlrev_b32_e32 v140, 16, v211
	v_and_b32_e32 v141, 0xffff0000, v211
	v_pk_mul_f32 v[142:143], v[134:135], v[134:135]
	v_pk_mul_f32 v[144:145], v[136:137], v[136:137]
	v_pk_mul_f32 v[248:249], v[138:139], v[138:139]
	v_pk_mul_f32 v[250:251], v[140:141], v[140:141]
	v_add_f32_e32 v208, v134, v135
	v_add_f32_e32 v209, v142, v143
	v_add_f32_e32 v158, v136, v137
	v_add_f32_e32 v159, v144, v145
	v_add_f32_e32 v160, v138, v139
	v_add_f32_e32 v161, v248, v249
	v_add_f32_e32 v162, v140, v141
	v_add_f32_e32 v163, v250, v251
	v_pk_add_f32 v[208:209], v[208:209], v[158:159]
	v_pk_add_f32 v[208:209], v[208:209], v[160:161]
	v_pk_add_f32 v[208:209], v[208:209], v[162:163]
	ds_read_b128 v[240:243], v152 offset:16128
	s_waitcnt lgkmcnt(7)
	v_lshlrev_b32_e32 v134, 16, v212
	v_and_b32_e32 v135, 0xffff0000, v212
	v_lshlrev_b32_e32 v136, 16, v213
	v_and_b32_e32 v137, 0xffff0000, v213
	v_lshlrev_b32_e32 v138, 16, v214
	v_and_b32_e32 v139, 0xffff0000, v214
	v_lshlrev_b32_e32 v140, 16, v215
	v_and_b32_e32 v141, 0xffff0000, v215
	v_pk_mul_f32 v[142:143], v[134:135], v[134:135]
	v_pk_mul_f32 v[144:145], v[136:137], v[136:137]
	v_pk_mul_f32 v[248:249], v[138:139], v[138:139]
	v_pk_mul_f32 v[250:251], v[140:141], v[140:141]
	v_add_f32_e32 v212, v134, v135
	v_add_f32_e32 v213, v142, v143
	v_add_f32_e32 v158, v136, v137
	v_add_f32_e32 v159, v144, v145
	v_add_f32_e32 v160, v138, v139
	v_add_f32_e32 v161, v248, v249
	v_add_f32_e32 v162, v140, v141
	v_add_f32_e32 v163, v250, v251
	v_pk_add_f32 v[212:213], v[212:213], v[158:159]
	v_pk_add_f32 v[212:213], v[212:213], v[160:161]
	v_pk_add_f32 v[212:213], v[212:213], v[162:163]
	ds_read_b128 v[244:247], v152 offset:17280
	s_nop 1
	v_add_f32_dpp v208, v208, v208 quad_perm:[1,0,3,2] row_mask:0xf bank_mask:0xf
	v_add_f32_dpp v209, v209, v209 quad_perm:[1,0,3,2] row_mask:0xf bank_mask:0xf
	v_add_f32_dpp v212, v212, v212 quad_perm:[1,0,3,2] row_mask:0xf bank_mask:0xf
	v_add_f32_dpp v213, v213, v213 quad_perm:[1,0,3,2] row_mask:0xf bank_mask:0xf
	v_add_f32_dpp v208, v208, v208 quad_perm:[2,3,0,1] row_mask:0xf bank_mask:0xf
	v_add_f32_dpp v209, v209, v209 quad_perm:[2,3,0,1] row_mask:0xf bank_mask:0xf
	v_add_f32_dpp v212, v212, v212 quad_perm:[2,3,0,1] row_mask:0xf bank_mask:0xf
	v_add_f32_dpp v213, v213, v213 quad_perm:[2,3,0,1] row_mask:0xf bank_mask:0xf
	v_add_f32_dpp v208, v208, v208 row_half_mirror row_mask:0xf bank_mask:0xf
	v_add_f32_dpp v209, v209, v209 row_half_mirror row_mask:0xf bank_mask:0xf
	v_add_f32_dpp v212, v212, v212 row_half_mirror row_mask:0xf bank_mask:0xf
	v_add_f32_dpp v213, v213, v213 row_half_mirror row_mask:0xf bank_mask:0xf
	s_waitcnt lgkmcnt(7)
	v_lshlrev_b32_e32 v134, 16, v216
	v_and_b32_e32 v135, 0xffff0000, v216
	v_lshlrev_b32_e32 v136, 16, v217
	v_and_b32_e32 v137, 0xffff0000, v217
	v_lshlrev_b32_e32 v138, 16, v218
	v_and_b32_e32 v139, 0xffff0000, v218
	v_lshlrev_b32_e32 v140, 16, v219
	v_and_b32_e32 v141, 0xffff0000, v219
	v_pk_mul_f32 v[142:143], v[134:135], v[134:135]
	v_pk_mul_f32 v[144:145], v[136:137], v[136:137]
	v_pk_mul_f32 v[248:249], v[138:139], v[138:139]
	v_pk_mul_f32 v[250:251], v[140:141], v[140:141]
	v_add_f32_e32 v216, v134, v135
	v_add_f32_e32 v217, v142, v143
	v_add_f32_e32 v158, v136, v137
	v_add_f32_e32 v159, v144, v145
	v_add_f32_e32 v160, v138, v139
	v_add_f32_e32 v161, v248, v249
	v_add_f32_e32 v162, v140, v141
	v_add_f32_e32 v163, v250, v251
	v_pk_add_f32 v[216:217], v[216:217], v[158:159]
	v_pk_add_f32 v[216:217], v[216:217], v[160:161]
	v_pk_add_f32 v[216:217], v[216:217], v[162:163]
	s_waitcnt lgkmcnt(6)
	v_lshlrev_b32_e32 v134, 16, v220
	v_and_b32_e32 v135, 0xffff0000, v220
	v_lshlrev_b32_e32 v136, 16, v221
	v_and_b32_e32 v137, 0xffff0000, v221
	v_lshlrev_b32_e32 v138, 16, v222
	v_and_b32_e32 v139, 0xffff0000, v222
	v_lshlrev_b32_e32 v140, 16, v223
	v_and_b32_e32 v141, 0xffff0000, v223
	v_pk_mul_f32 v[142:143], v[134:135], v[134:135]
	v_pk_mul_f32 v[144:145], v[136:137], v[136:137]
	v_pk_mul_f32 v[248:249], v[138:139], v[138:139]
	v_pk_mul_f32 v[250:251], v[140:141], v[140:141]
	v_add_f32_e32 v220, v134, v135
	v_add_f32_e32 v221, v142, v143
	v_add_f32_e32 v158, v136, v137
	v_add_f32_e32 v159, v144, v145
	v_add_f32_e32 v160, v138, v139
	v_add_f32_e32 v161, v248, v249
	v_add_f32_e32 v162, v140, v141
	v_add_f32_e32 v163, v250, v251
	v_pk_add_f32 v[220:221], v[220:221], v[158:159]
	v_pk_add_f32 v[220:221], v[220:221], v[160:161]
	v_pk_add_f32 v[220:221], v[220:221], v[162:163]
	s_nop 1
	v_add_f32_dpp v216, v216, v216 quad_perm:[1,0,3,2] row_mask:0xf bank_mask:0xf
	v_add_f32_dpp v217, v217, v217 quad_perm:[1,0,3,2] row_mask:0xf bank_mask:0xf
	v_add_f32_dpp v220, v220, v220 quad_perm:[1,0,3,2] row_mask:0xf bank_mask:0xf
	v_add_f32_dpp v221, v221, v221 quad_perm:[1,0,3,2] row_mask:0xf bank_mask:0xf
	v_add_f32_dpp v216, v216, v216 quad_perm:[2,3,0,1] row_mask:0xf bank_mask:0xf
	v_add_f32_dpp v217, v217, v217 quad_perm:[2,3,0,1] row_mask:0xf bank_mask:0xf
	v_add_f32_dpp v220, v220, v220 quad_perm:[2,3,0,1] row_mask:0xf bank_mask:0xf
	v_add_f32_dpp v221, v221, v221 quad_perm:[2,3,0,1] row_mask:0xf bank_mask:0xf
	v_add_f32_dpp v216, v216, v216 row_half_mirror row_mask:0xf bank_mask:0xf
	v_add_f32_dpp v217, v217, v217 row_half_mirror row_mask:0xf bank_mask:0xf
	v_add_f32_dpp v220, v220, v220 row_half_mirror row_mask:0xf bank_mask:0xf
	v_add_f32_dpp v221, v221, v221 row_half_mirror row_mask:0xf bank_mask:0xf
	s_waitcnt lgkmcnt(5)
	v_lshlrev_b32_e32 v134, 16, v224
	v_and_b32_e32 v135, 0xffff0000, v224
	v_lshlrev_b32_e32 v136, 16, v225
	v_and_b32_e32 v137, 0xffff0000, v225
	v_lshlrev_b32_e32 v138, 16, v226
	v_and_b32_e32 v139, 0xffff0000, v226
	v_lshlrev_b32_e32 v140, 16, v227
	v_and_b32_e32 v141, 0xffff0000, v227
	v_pk_mul_f32 v[142:143], v[134:135], v[134:135]
	v_pk_mul_f32 v[144:145], v[136:137], v[136:137]
	v_pk_mul_f32 v[248:249], v[138:139], v[138:139]
	v_pk_mul_f32 v[250:251], v[140:141], v[140:141]
	v_add_f32_e32 v224, v134, v135
	v_add_f32_e32 v225, v142, v143
	v_add_f32_e32 v158, v136, v137
	v_add_f32_e32 v159, v144, v145
	v_add_f32_e32 v160, v138, v139
	v_add_f32_e32 v161, v248, v249
	v_add_f32_e32 v162, v140, v141
	v_add_f32_e32 v163, v250, v251
	v_pk_add_f32 v[224:225], v[224:225], v[158:159]
	v_pk_add_f32 v[224:225], v[224:225], v[160:161]
	v_pk_add_f32 v[224:225], v[224:225], v[162:163]
	s_waitcnt lgkmcnt(4)
	v_lshlrev_b32_e32 v134, 16, v228
	v_and_b32_e32 v135, 0xffff0000, v228
	v_lshlrev_b32_e32 v136, 16, v229
	v_and_b32_e32 v137, 0xffff0000, v229
	v_lshlrev_b32_e32 v138, 16, v230
	v_and_b32_e32 v139, 0xffff0000, v230
	v_lshlrev_b32_e32 v140, 16, v231
	v_and_b32_e32 v141, 0xffff0000, v231
	v_pk_mul_f32 v[142:143], v[134:135], v[134:135]
	v_pk_mul_f32 v[144:145], v[136:137], v[136:137]
	v_pk_mul_f32 v[248:249], v[138:139], v[138:139]
	v_pk_mul_f32 v[250:251], v[140:141], v[140:141]
	v_add_f32_e32 v228, v134, v135
	v_add_f32_e32 v229, v142, v143
	v_add_f32_e32 v158, v136, v137
	v_add_f32_e32 v159, v144, v145
	v_add_f32_e32 v160, v138, v139
	v_add_f32_e32 v161, v248, v249
	v_add_f32_e32 v162, v140, v141
	v_add_f32_e32 v163, v250, v251
	v_pk_add_f32 v[228:229], v[228:229], v[158:159]
	v_pk_add_f32 v[228:229], v[228:229], v[160:161]
	v_pk_add_f32 v[228:229], v[228:229], v[162:163]
	s_nop 1
	v_add_f32_dpp v224, v224, v224 quad_perm:[1,0,3,2] row_mask:0xf bank_mask:0xf
	v_add_f32_dpp v225, v225, v225 quad_perm:[1,0,3,2] row_mask:0xf bank_mask:0xf
	v_add_f32_dpp v228, v228, v228 quad_perm:[1,0,3,2] row_mask:0xf bank_mask:0xf
	v_add_f32_dpp v229, v229, v229 quad_perm:[1,0,3,2] row_mask:0xf bank_mask:0xf
	v_add_f32_dpp v224, v224, v224 quad_perm:[2,3,0,1] row_mask:0xf bank_mask:0xf
	v_add_f32_dpp v225, v225, v225 quad_perm:[2,3,0,1] row_mask:0xf bank_mask:0xf
	v_add_f32_dpp v228, v228, v228 quad_perm:[2,3,0,1] row_mask:0xf bank_mask:0xf
	v_add_f32_dpp v229, v229, v229 quad_perm:[2,3,0,1] row_mask:0xf bank_mask:0xf
	v_add_f32_dpp v224, v224, v224 row_half_mirror row_mask:0xf bank_mask:0xf
	v_add_f32_dpp v225, v225, v225 row_half_mirror row_mask:0xf bank_mask:0xf
	v_add_f32_dpp v228, v228, v228 row_half_mirror row_mask:0xf bank_mask:0xf
	v_add_f32_dpp v229, v229, v229 row_half_mirror row_mask:0xf bank_mask:0xf
	s_waitcnt lgkmcnt(3)
	v_lshlrev_b32_e32 v134, 16, v232
	v_and_b32_e32 v135, 0xffff0000, v232
	v_lshlrev_b32_e32 v136, 16, v233
	v_and_b32_e32 v137, 0xffff0000, v233
	v_lshlrev_b32_e32 v138, 16, v234
	v_and_b32_e32 v139, 0xffff0000, v234
	v_lshlrev_b32_e32 v140, 16, v235
	v_and_b32_e32 v141, 0xffff0000, v235
	v_pk_mul_f32 v[142:143], v[134:135], v[134:135]
	v_pk_mul_f32 v[144:145], v[136:137], v[136:137]
	v_pk_mul_f32 v[248:249], v[138:139], v[138:139]
	v_pk_mul_f32 v[250:251], v[140:141], v[140:141]
	v_add_f32_e32 v232, v134, v135
	v_add_f32_e32 v233, v142, v143
	v_add_f32_e32 v158, v136, v137
	v_add_f32_e32 v159, v144, v145
	v_add_f32_e32 v160, v138, v139
	v_add_f32_e32 v161, v248, v249
	v_add_f32_e32 v162, v140, v141
	v_add_f32_e32 v163, v250, v251
	v_pk_add_f32 v[232:233], v[232:233], v[158:159]
	v_pk_add_f32 v[232:233], v[232:233], v[160:161]
	v_pk_add_f32 v[232:233], v[232:233], v[162:163]
	s_waitcnt lgkmcnt(2)
	v_lshlrev_b32_e32 v134, 16, v236
	v_and_b32_e32 v135, 0xffff0000, v236
	v_lshlrev_b32_e32 v136, 16, v237
	v_and_b32_e32 v137, 0xffff0000, v237
	v_lshlrev_b32_e32 v138, 16, v238
	v_and_b32_e32 v139, 0xffff0000, v238
	v_lshlrev_b32_e32 v140, 16, v239
	v_and_b32_e32 v141, 0xffff0000, v239
	v_pk_mul_f32 v[142:143], v[134:135], v[134:135]
	v_pk_mul_f32 v[144:145], v[136:137], v[136:137]
	v_pk_mul_f32 v[248:249], v[138:139], v[138:139]
	v_pk_mul_f32 v[250:251], v[140:141], v[140:141]
	v_add_f32_e32 v236, v134, v135
	v_add_f32_e32 v237, v142, v143
	v_add_f32_e32 v158, v136, v137
	v_add_f32_e32 v159, v144, v145
	v_add_f32_e32 v160, v138, v139
	v_add_f32_e32 v161, v248, v249
	v_add_f32_e32 v162, v140, v141
	v_add_f32_e32 v163, v250, v251
	v_pk_add_f32 v[236:237], v[236:237], v[158:159]
	v_pk_add_f32 v[236:237], v[236:237], v[160:161]
	v_pk_add_f32 v[236:237], v[236:237], v[162:163]
	s_nop 1
	v_add_f32_dpp v232, v232, v232 quad_perm:[1,0,3,2] row_mask:0xf bank_mask:0xf
	v_add_f32_dpp v233, v233, v233 quad_perm:[1,0,3,2] row_mask:0xf bank_mask:0xf
	v_add_f32_dpp v236, v236, v236 quad_perm:[1,0,3,2] row_mask:0xf bank_mask:0xf
	v_add_f32_dpp v237, v237, v237 quad_perm:[1,0,3,2] row_mask:0xf bank_mask:0xf
	v_add_f32_dpp v232, v232, v232 quad_perm:[2,3,0,1] row_mask:0xf bank_mask:0xf
	v_add_f32_dpp v233, v233, v233 quad_perm:[2,3,0,1] row_mask:0xf bank_mask:0xf
	v_add_f32_dpp v236, v236, v236 quad_perm:[2,3,0,1] row_mask:0xf bank_mask:0xf
	v_add_f32_dpp v237, v237, v237 quad_perm:[2,3,0,1] row_mask:0xf bank_mask:0xf
	v_add_f32_dpp v232, v232, v232 row_half_mirror row_mask:0xf bank_mask:0xf
	v_add_f32_dpp v233, v233, v233 row_half_mirror row_mask:0xf bank_mask:0xf
	v_add_f32_dpp v236, v236, v236 row_half_mirror row_mask:0xf bank_mask:0xf
	v_add_f32_dpp v237, v237, v237 row_half_mirror row_mask:0xf bank_mask:0xf
	s_waitcnt lgkmcnt(1)
	v_lshlrev_b32_e32 v134, 16, v240
	v_and_b32_e32 v135, 0xffff0000, v240
	v_lshlrev_b32_e32 v136, 16, v241
	v_and_b32_e32 v137, 0xffff0000, v241
	v_lshlrev_b32_e32 v138, 16, v242
	v_and_b32_e32 v139, 0xffff0000, v242
	v_lshlrev_b32_e32 v140, 16, v243
	v_and_b32_e32 v141, 0xffff0000, v243
	v_pk_mul_f32 v[142:143], v[134:135], v[134:135]
	v_pk_mul_f32 v[144:145], v[136:137], v[136:137]
	v_pk_mul_f32 v[248:249], v[138:139], v[138:139]
	v_pk_mul_f32 v[250:251], v[140:141], v[140:141]
	v_add_f32_e32 v240, v134, v135
	v_add_f32_e32 v241, v142, v143
	v_add_f32_e32 v158, v136, v137
	v_add_f32_e32 v159, v144, v145
	v_add_f32_e32 v160, v138, v139
	v_add_f32_e32 v161, v248, v249
	v_add_f32_e32 v162, v140, v141
	v_add_f32_e32 v163, v250, v251
	v_pk_add_f32 v[240:241], v[240:241], v[158:159]
	v_pk_add_f32 v[240:241], v[240:241], v[160:161]
	v_pk_add_f32 v[240:241], v[240:241], v[162:163]
	s_waitcnt lgkmcnt(0)
	v_lshlrev_b32_e32 v134, 16, v244
	v_and_b32_e32 v135, 0xffff0000, v244
	v_lshlrev_b32_e32 v136, 16, v245
	v_and_b32_e32 v137, 0xffff0000, v245
	v_lshlrev_b32_e32 v138, 16, v246
	v_and_b32_e32 v139, 0xffff0000, v246
	v_lshlrev_b32_e32 v140, 16, v247
	v_and_b32_e32 v141, 0xffff0000, v247
	v_pk_mul_f32 v[142:143], v[134:135], v[134:135]
	v_pk_mul_f32 v[144:145], v[136:137], v[136:137]
	v_pk_mul_f32 v[248:249], v[138:139], v[138:139]
	v_pk_mul_f32 v[250:251], v[140:141], v[140:141]
	v_add_f32_e32 v244, v134, v135
	v_add_f32_e32 v245, v142, v143
	v_add_f32_e32 v158, v136, v137
	v_add_f32_e32 v159, v144, v145
	v_add_f32_e32 v160, v138, v139
	v_add_f32_e32 v161, v248, v249
	v_add_f32_e32 v162, v140, v141
	v_add_f32_e32 v163, v250, v251
	v_pk_add_f32 v[244:245], v[244:245], v[158:159]
	v_pk_add_f32 v[244:245], v[244:245], v[160:161]
	v_pk_add_f32 v[244:245], v[244:245], v[162:163]
	s_nop 1
	v_add_f32_dpp v240, v240, v240 quad_perm:[1,0,3,2] row_mask:0xf bank_mask:0xf
	v_add_f32_dpp v241, v241, v241 quad_perm:[1,0,3,2] row_mask:0xf bank_mask:0xf
	v_add_f32_dpp v244, v244, v244 quad_perm:[1,0,3,2] row_mask:0xf bank_mask:0xf
	v_add_f32_dpp v245, v245, v245 quad_perm:[1,0,3,2] row_mask:0xf bank_mask:0xf
	v_add_f32_dpp v240, v240, v240 quad_perm:[2,3,0,1] row_mask:0xf bank_mask:0xf
	v_add_f32_dpp v241, v241, v241 quad_perm:[2,3,0,1] row_mask:0xf bank_mask:0xf
	v_add_f32_dpp v244, v244, v244 quad_perm:[2,3,0,1] row_mask:0xf bank_mask:0xf
	v_add_f32_dpp v245, v245, v245 quad_perm:[2,3,0,1] row_mask:0xf bank_mask:0xf
	v_add_f32_dpp v240, v240, v240 row_half_mirror row_mask:0xf bank_mask:0xf
	v_add_f32_dpp v241, v241, v241 row_half_mirror row_mask:0xf bank_mask:0xf
	v_add_f32_dpp v244, v244, v244 row_half_mirror row_mask:0xf bank_mask:0xf
	v_add_f32_dpp v245, v245, v245 row_half_mirror row_mask:0xf bank_mask:0xf
	s_and_saveexec_b64 s[44:45], s[0:1]
	global_store_dwordx2 v129, v[184:185], s[6:7]
	v_add_u32_e32 v129, 0x800, v129
	global_store_dwordx2 v129, v[188:189], s[6:7]
	v_add_u32_e32 v129, 0x800, v129
	global_store_dwordx2 v129, v[192:193], s[6:7]
	v_add_u32_e32 v129, 0x800, v129
	global_store_dwordx2 v129, v[196:197], s[6:7]
	v_add_u32_e32 v129, 0x800, v129
	global_store_dwordx2 v129, v[200:201], s[6:7]
	v_add_u32_e32 v129, 0x800, v129
	global_store_dwordx2 v129, v[204:205], s[6:7]
	v_add_u32_e32 v129, 0x800, v129
	global_store_dwordx2 v129, v[208:209], s[6:7]
	v_add_u32_e32 v129, 0x800, v129
	global_store_dwordx2 v129, v[212:213], s[6:7]
	v_add_u32_e32 v129, 0x800, v129
	global_store_dwordx2 v129, v[216:217], s[6:7]
	v_add_u32_e32 v129, 0x800, v129
	global_store_dwordx2 v129, v[220:221], s[6:7]
	v_add_u32_e32 v129, 0x800, v129
	global_store_dwordx2 v129, v[224:225], s[6:7]
	v_add_u32_e32 v129, 0x800, v129
	global_store_dwordx2 v129, v[228:229], s[6:7]
	v_add_u32_e32 v129, 0x800, v129
	global_store_dwordx2 v129, v[232:233], s[6:7]
	v_add_u32_e32 v129, 0x800, v129
	global_store_dwordx2 v129, v[236:237], s[6:7]
	v_add_u32_e32 v129, 0x800, v129
	global_store_dwordx2 v129, v[240:241], s[6:7]
	v_add_u32_e32 v129, 0x800, v129
	global_store_dwordx2 v129, v[244:245], s[6:7]
	s_or_b64 exec, exec, s[44:45]
	s_waitcnt lgkmcnt(0)
